# v23 + hand-written resid1 row loop (coalesced dwordx4 loads/stores, next-row prefetch, f32 math same as baseline)
# speedup vs baseline: 1.0068x; 1.0004x over previous
; __device__ __forceinline__ void resid_rows(bf16* __restrict__ XB, const bf16* __restrict__ Y, const float* __restrict__ PART, const float* __restrict__ g, float* __restrict__ RS, ...
;     f32x4 gv[16];
; #pragma unroll
;     for (int j = 0; j < 16; ++j) gv[j] = *(const f32x4*)(g + (lane + 64 * j) * 4);
;     for (int m = gw; m < MTOK; m += NGW) {
;         const float pv = PART[(size_t)m * 64 + lane];
;         bf16* xrow = XB + (size_t)m * DM; const bf16* yrow = Y + (size_t)m * DM;
;         v2u xr[16], yr[16];
; #pragma unroll
;         for (int j = 0; j < 16; ++j) { xr[j] = *(const v2u*)(xrow + (lane + 64 * j) * 4); yr[j] = *(const v2u*)(yrow + (lane + 64 * j) * 4); }
;         const float ry = 1.0f / sqrtf(wave_sum(pv) * (1.0f / DM) + EPS);
.LBB0_812:
	s_waitcnt vmcnt(0)
	s_lshl_b32 s14, s1, 3
	s_load_dwordx2 s[30:31], s[2:3], 0x10
	s_load_dwordx2 s[18:19], s[2:3], 0x88
	s_lshl_b32 s12, s22, 14
	v_lshlrev_b32_e32 v192, 4, v82
	v_lshlrev_b32_e32 v194, 3, v82
	v_lshlrev_b32_e32 v195, 2, v82
	v_lshlrev_b32_e32 v238, 5, v82
	v_mov_b32_e32 v196, 0
	v_add_u32_e32 v193, 0x1000, v192
	v_mov_b32_e32 v206, 0x4b400000
	v_mov_b32_e32 v207, 0x4b400000
	s_mov_b32 s57, 0x42fe0000
	s_mov_b32 s58, 0x1e3ce508
	s_mov_b32 s59, 0xf800000
	s_mov_b32 s60, 0x0c0c0400
	s_mov_b32 s61, 0x04000c0c
	s_waitcnt lgkmcnt(0)
	s_add_u32 s30, s30, s12
	s_addc_u32 s31, s31, 0
	s_add_u32 s76, s18, 0x2d800000
	s_addc_u32 s77, s19, 0
	s_add_u32 s78, s18, 0x56800000
	s_addc_u32 s79, s19, 0
	s_lshl_b32 s0, s8, 8
	s_add_u32 s4, s18, s0
	s_addc_u32 s5, s19, 0
	s_add_u32 s4, s4, 0x400000
	s_addc_u32 s5, s5, 0
	global_load_dword v250, v195, s[4:5]
	s_lshl_b32 s0, s8, 13
	s_add_u32 s24, s76, s0
	s_addc_u32 s25, s77, 0
	s_add_u32 s26, s24, 0x11000000
	s_addc_u32 s27, s25, 0
	global_load_dwordx4 v[64:67], v192, s[24:25] offset:0 nt
	global_load_dwordx4 v[68:71], v192, s[26:27] offset:0 nt
	global_load_dwordx4 v[72:75], v192, s[24:25] offset:1024 nt
	global_load_dwordx4 v[76:79], v192, s[26:27] offset:1024 nt
	global_load_dwordx4 v[80:83], v192, s[24:25] offset:2048 nt
	global_load_dwordx4 v[84:87], v192, s[26:27] offset:2048 nt
	global_load_dwordx4 v[88:91], v192, s[24:25] offset:3072 nt
	global_load_dwordx4 v[92:95], v192, s[26:27] offset:3072 nt
	global_load_dwordx4 v[96:99], v193, s[24:25] offset:0 nt
	global_load_dwordx4 v[100:103], v193, s[26:27] offset:0 nt
	global_load_dwordx4 v[104:107], v193, s[24:25] offset:1024 nt
	global_load_dwordx4 v[108:111], v193, s[26:27] offset:1024 nt
	global_load_dwordx4 v[112:115], v193, s[24:25] offset:2048 nt
	global_load_dwordx4 v[116:119], v193, s[26:27] offset:2048 nt
	global_load_dwordx4 v[120:123], v193, s[24:25] offset:3072 nt
	global_load_dwordx4 v[124:127], v193, s[26:27] offset:3072 nt
	global_load_dwordx4 v[0:3], v238, s[30:31] offset:0
	global_load_dwordx4 v[4:7], v238, s[30:31] offset:16
	global_load_dwordx4 v[8:11], v238, s[30:31] offset:2048
	global_load_dwordx4 v[12:15], v238, s[30:31] offset:2064
	s_add_u32 s30, s30, 0x1000
	s_addc_u32 s31, s31, 0
	global_load_dwordx4 v[16:19], v238, s[30:31] offset:0
	global_load_dwordx4 v[20:23], v238, s[30:31] offset:16
	global_load_dwordx4 v[24:27], v238, s[30:31] offset:2048
	global_load_dwordx4 v[28:31], v238, s[30:31] offset:2064
	s_add_u32 s30, s30, 0x1000
	s_addc_u32 s31, s31, 0
	global_load_dwordx4 v[32:35], v238, s[30:31] offset:0
	global_load_dwordx4 v[36:39], v238, s[30:31] offset:16
	global_load_dwordx4 v[40:43], v238, s[30:31] offset:2048
	global_load_dwordx4 v[44:47], v238, s[30:31] offset:2064
	s_add_u32 s30, s30, 0x1000
	s_addc_u32 s31, s31, 0
	global_load_dwordx4 v[48:51], v238, s[30:31] offset:0
	global_load_dwordx4 v[52:55], v238, s[30:31] offset:16
	global_load_dwordx4 v[56:59], v238, s[30:31] offset:2048
	global_load_dwordx4 v[60:63], v238, s[30:31] offset:2064
	s_waitcnt vmcnt(32)
	ds_swizzle_b32 v241, v250 offset:swizzle(SWAP,1)
	s_nop 0
	s_waitcnt lgkmcnt(0)
	v_add_f32_e32 v250, v250, v241
	ds_swizzle_b32 v241, v250 offset:swizzle(SWAP,2)
	s_nop 0
	s_waitcnt lgkmcnt(0)
	v_add_f32_e32 v250, v250, v241
	ds_swizzle_b32 v241, v250 offset:swizzle(SWAP,4)
	s_nop 0
	s_waitcnt lgkmcnt(0)
	v_add_f32_e32 v250, v250, v241
	ds_swizzle_b32 v241, v250 offset:swizzle(SWAP,8)
	s_nop 0
	s_waitcnt lgkmcnt(0)
	v_add_f32_e32 v250, v250, v241
	ds_swizzle_b32 v241, v250 offset:swizzle(SWAP,16)
	s_nop 0
	s_waitcnt lgkmcnt(0)
	v_add_f32_e32 v250, v250, v241
	v_mov_b32_e32 v241, v250
	s_nop 1
	v_permlane32_swap_b32_e32 v250, v241
	v_add_f32_e32 v250, v250, v241
	v_fmamk_f32 v212, v250, 0x39800000, v216
	v_mul_f32_e32 v213, 0x4f800000, v212
	v_cmp_gt_f32_e32 vcc, s59, v212
	s_nop 1
	v_cndmask_b32_e32 v214, v212, v213, vcc
	v_sqrt_f32_e32 v215, v214
	s_nop 0
	s_nop 0
	v_add_u32_e32 v246, -1, v215
	v_fma_f32 v247, -v246, v215, v214
	v_cmp_ge_f32_e64 s[62:63], 0, v247
	v_add_u32_e32 v247, 1, v215
	v_fma_f32 v248, -v247, v215, v214
	v_cndmask_b32_e64 v246, v215, v246, s[62:63]
	v_cmp_lt_f32_e64 s[62:63], 0, v248
	s_nop 1
	v_cndmask_b32_e64 v246, v246, v247, s[62:63]
	v_mul_f32_e32 v247, 0x37800000, v246
	v_cndmask_b32_e32 v246, v246, v247, vcc
	v_cmp_class_f32_e32 vcc, v214, v239
	s_nop 1
	v_cndmask_b32_e32 v248, v246, v214, vcc
	v_div_scale_f32 v249, s[0:1], v248, v248, 1.0
	v_rcp_f32_e32 v212, v249
	s_nop 0
	v_fma_f32 v213, -v249, v212, 1.0
	v_fmac_f32_e32 v212, v213, v212
	v_div_scale_f32 v213, vcc, 1.0, v248, 1.0
	v_mul_f32_e32 v214, v213, v212
	v_fma_f32 v215, -v249, v214, v213
	v_fmac_f32_e32 v214, v215, v212
	v_fma_f32 v213, -v249, v214, v213
	v_div_fmas_f32 v213, v213, v212, v214
	v_div_fixup_f32 v200, v213, v248, 1.0
	s_waitcnt vmcnt(0)
	s_branch .Lr1_A_go

; template <int OFF = 0, class V> __device__ __forceinline__ void st_wt16(void* p, V v) { static_assert(sizeof(V) == 16, ""); asm volatile("global_store_dwordx4 %0, %1, off offset:%2 sc1\n\ts_nop 1" :: "v"(p), "v"(v), "i"(OFF)); }
; template <int OFF = 0, class V> __device__ __forceinline__ void st_wt8(void* p, V v) { static_assert(sizeof(V) == 8, ""); asm volatile("global_store_dwordx2 %0, %1, off offset:%2 sc1\n\ts_nop 1" :: "v"(p), "v"(v), "i"(OFF)); }
; __device__ __forceinline__ unsigned pk2(float lo, float hi) { return pg8::cvt_pk_bf16(lo, hi); }
; __device__ __forceinline__ float bf_lo(unsigned w) { return __uint_as_float(w << 16); }
; __device__ __forceinline__ float bf_hi(unsigned w) { return __uint_as_float(w & 0xffff0000u); }
; __device__ __forceinline__ void resid_rows(bf16* __restrict__ XB, const bf16* __restrict__ Y, const float* __restrict__ PART, const float* __restrict__ g, float* __restrict__ RS, ...
;     ...
;     for (int m = gw; m < MTOK; m += NGW) {
;         const float pv = PART[(size_t)m * 64 + lane];
;         bf16* xrow = XB + (size_t)m * DM; const bf16* yrow = Y + (size_t)m * DM;
;         v2u xr[16], yr[16];
; #pragma unroll
;         for (int j = 0; j < 16; ++j) { xr[j] = *(const v2u*)(xrow + (lane + 64 * j) * 4); yr[j] = *(const v2u*)(yrow + (lane + 64 * j) * 4); }
;         const float ry = 1.0f / sqrtf(wave_sum(pv) * (1.0f / DM) + EPS);
;         float ss = 0.f, am = 0.f; f32x4 ov[16];
; #pragma unroll
;         for (int j = 0; j < 16; ++j) { const int c = (lane + 64 * j) * 4;
;             f32x4 o; o.x = bf_lo(xr[j].x) + bf_lo(yr[j].x) * ry * gv[j].x; o.y = bf_hi(xr[j].x) + bf_hi(yr[j].x) * ry * gv[j].y; o.z = bf_lo(xr[j].y) + bf_lo(yr[j].y) * ry * gv[j].z; o.w = bf_hi(xr[j].y) + bf_hi(yr[j].y) * ry * gv[j].w;
;             ss += (o.x * o.x + o.y * o.y) + (o.z * o.z + o.w * o.w); ov[j] = o; am = fmaxf(fmaxf(am, fmaxf(fabsf(o.x), fabsf(o.y))), fmaxf(fabsf(o.z), fabsf(o.w)));
;             if (outf) st_wt16(outf + (size_t)m * DM + c, o); else { v2u ob; ob.x = pk2(o.x, o.y); ob.y = pk2(o.z, o.w); st_wt8(xrow + c, ob); } }
.Lr1_A_go:
	v_mov_b32_e32 v198, v200
	v_mov_b32_e32 v199, v200
	s_lshl_b32 s0, s8, 13
	s_add_u32 s80, s76, s0
	s_addc_u32 s81, s77, 0
	s_lshl_b32 s0, s8, 12
	s_add_u32 s82, s78, s0
	s_addc_u32 s83, s79, 0
	s_lshl_b32 s0, s8, 2
	s_add_u32 s84, s18, s0
	s_addc_u32 s85, s19, 0
	s_add_u32 s84, s84, 0x100000
	s_addc_u32 s85, s85, 0
	s_add_u32 s86, s84, 0x10000
	s_addc_u32 s87, s85, 0
	s_add_i32 s9, s8, s14
	s_cmpk_lt_i32 s9, 0x2000
	s_cselect_b32 s16, 1, 0
	v_mov_b32_e32 v251, 1.0
	s_cbranch_scc0 .Lr1_A_noissue
	s_lshl_b32 s0, s9, 8
	s_add_u32 s4, s18, s0
	s_addc_u32 s5, s19, 0
	s_add_u32 s4, s4, 0x400000
	s_addc_u32 s5, s5, 0
	global_load_dword v251, v195, s[4:5]
	s_lshl_b32 s0, s9, 13
	s_add_u32 s24, s76, s0
	s_addc_u32 s25, s77, 0
	s_add_u32 s26, s24, 0x11000000
	s_addc_u32 s27, s25, 0
	global_load_dwordx4 v[128:131], v192, s[24:25] offset:0 nt
	global_load_dwordx4 v[132:135], v192, s[26:27] offset:0 nt
	global_load_dwordx4 v[136:139], v192, s[24:25] offset:1024 nt
	global_load_dwordx4 v[140:143], v192, s[26:27] offset:1024 nt
	global_load_dwordx4 v[144:147], v192, s[24:25] offset:2048 nt
	global_load_dwordx4 v[148:151], v192, s[26:27] offset:2048 nt
	global_load_dwordx4 v[152:155], v192, s[24:25] offset:3072 nt
	global_load_dwordx4 v[156:159], v192, s[26:27] offset:3072 nt
	global_load_dwordx4 v[160:163], v193, s[24:25] offset:0 nt
	global_load_dwordx4 v[164:167], v193, s[26:27] offset:0 nt
	global_load_dwordx4 v[168:171], v193, s[24:25] offset:1024 nt
	global_load_dwordx4 v[172:175], v193, s[26:27] offset:1024 nt
	global_load_dwordx4 v[176:179], v193, s[24:25] offset:2048 nt
	global_load_dwordx4 v[180:183], v193, s[26:27] offset:2048 nt
	global_load_dwordx4 v[184:187], v193, s[24:25] offset:3072 nt
	global_load_dwordx4 v[188:191], v193, s[26:27] offset:3072 nt
.Lr1_A_noissue:
	v_mov_b32_e32 v197, 0
	v_mov_b32_e32 v202, 0
	v_mov_b32_e32 v203, 0
	v_lshlrev_b32_e32 v208, 16, v68
	v_and_b32_e32 v209, 0xffff0000, v68
	v_pk_mul_f32 v[208:209], v[198:199], v[208:209]
	v_lshlrev_b32_e32 v220, 16, v64
	v_and_b32_e32 v221, 0xffff0000, v64
	v_pk_fma_f32 v[220:221], v[0:1], v[208:209], v[220:221]
	v_max3_f32 v197, v197, |v220|, |v221|
	v_pk_fma_f32 v[202:203], v[220:221], v[220:221], v[202:203]
	v_cvt_pk_bf16_f32 v212, v220, v221
	v_lshlrev_b32_e32 v210, 16, v69
	v_and_b32_e32 v211, 0xffff0000, v69
	v_pk_mul_f32 v[210:211], v[198:199], v[210:211]
	v_lshlrev_b32_e32 v222, 16, v65
	v_and_b32_e32 v223, 0xffff0000, v65
	v_pk_fma_f32 v[222:223], v[2:3], v[210:211], v[222:223]
	v_max3_f32 v197, v197, |v222|, |v223|
	v_pk_fma_f32 v[202:203], v[222:223], v[222:223], v[202:203]
	v_cvt_pk_bf16_f32 v213, v222, v223
	v_lshlrev_b32_e32 v208, 16, v70
	v_and_b32_e32 v209, 0xffff0000, v70
	v_pk_mul_f32 v[208:209], v[198:199], v[208:209]
	v_lshlrev_b32_e32 v224, 16, v66
	v_and_b32_e32 v225, 0xffff0000, v66
	v_pk_fma_f32 v[224:225], v[4:5], v[208:209], v[224:225]
	v_max3_f32 v197, v197, |v224|, |v225|
	v_pk_fma_f32 v[202:203], v[224:225], v[224:225], v[202:203]
	v_cvt_pk_bf16_f32 v214, v224, v225
	v_lshlrev_b32_e32 v210, 16, v71
	v_and_b32_e32 v211, 0xffff0000, v71
	v_pk_mul_f32 v[210:211], v[198:199], v[210:211]
	v_lshlrev_b32_e32 v226, 16, v67
	v_and_b32_e32 v227, 0xffff0000, v67
	v_pk_fma_f32 v[226:227], v[6:7], v[210:211], v[226:227]
	v_max3_f32 v197, v197, |v226|, |v227|
	v_pk_fma_f32 v[202:203], v[226:227], v[226:227], v[202:203]
	v_cvt_pk_bf16_f32 v215, v226, v227
	global_store_dwordx4 v192, v[212:215], s[80:81] offset:0 sc1 nt
	v_lshlrev_b32_e32 v208, 16, v76
	v_and_b32_e32 v209, 0xffff0000, v76
	v_pk_mul_f32 v[208:209], v[198:199], v[208:209]
	v_lshlrev_b32_e32 v64, 16, v72
	v_and_b32_e32 v65, 0xffff0000, v72
	v_pk_fma_f32 v[64:65], v[8:9], v[208:209], v[64:65]
	v_max3_f32 v197, v197, |v64|, |v65|
	v_pk_fma_f32 v[202:203], v[64:65], v[64:65], v[202:203]
	v_cvt_pk_bf16_f32 v246, v64, v65
	v_lshlrev_b32_e32 v210, 16, v77
	v_and_b32_e32 v211, 0xffff0000, v77
	v_pk_mul_f32 v[210:211], v[198:199], v[210:211]
	v_lshlrev_b32_e32 v66, 16, v73
	v_and_b32_e32 v67, 0xffff0000, v73
	v_pk_fma_f32 v[66:67], v[10:11], v[210:211], v[66:67]
	v_max3_f32 v197, v197, |v66|, |v67|
	v_pk_fma_f32 v[202:203], v[66:67], v[66:67], v[202:203]
	v_cvt_pk_bf16_f32 v247, v66, v67
	v_lshlrev_b32_e32 v208, 16, v78
	v_and_b32_e32 v209, 0xffff0000, v78
	v_pk_mul_f32 v[208:209], v[198:199], v[208:209]
	v_lshlrev_b32_e32 v68, 16, v74
	v_and_b32_e32 v69, 0xffff0000, v74
	v_pk_fma_f32 v[68:69], v[12:13], v[208:209], v[68:69]
	v_max3_f32 v197, v197, |v68|, |v69|
	v_pk_fma_f32 v[202:203], v[68:69], v[68:69], v[202:203]
	v_cvt_pk_bf16_f32 v248, v68, v69
	v_lshlrev_b32_e32 v210, 16, v79
	v_and_b32_e32 v211, 0xffff0000, v79
	v_pk_mul_f32 v[210:211], v[198:199], v[210:211]
	v_lshlrev_b32_e32 v70, 16, v75
	v_and_b32_e32 v71, 0xffff0000, v75
	v_pk_fma_f32 v[70:71], v[14:15], v[210:211], v[70:71]
	v_max3_f32 v197, v197, |v70|, |v71|
	v_pk_fma_f32 v[202:203], v[70:71], v[70:71], v[202:203]
	v_cvt_pk_bf16_f32 v249, v70, v71
	global_store_dwordx4 v192, v[246:249], s[80:81] offset:1024 sc1 nt
	v_lshlrev_b32_e32 v208, 16, v84
	v_and_b32_e32 v209, 0xffff0000, v84
	v_pk_mul_f32 v[208:209], v[198:199], v[208:209]
	v_lshlrev_b32_e32 v72, 16, v80
	v_and_b32_e32 v73, 0xffff0000, v80
	v_pk_fma_f32 v[72:73], v[16:17], v[208:209], v[72:73]
	v_max3_f32 v197, v197, |v72|, |v73|
	v_pk_fma_f32 v[202:203], v[72:73], v[72:73], v[202:203]
	v_cvt_pk_bf16_f32 v212, v72, v73
	v_lshlrev_b32_e32 v210, 16, v85
	v_and_b32_e32 v211, 0xffff0000, v85
	v_pk_mul_f32 v[210:211], v[198:199], v[210:211]
	v_lshlrev_b32_e32 v74, 16, v81
	v_and_b32_e32 v75, 0xffff0000, v81
	v_pk_fma_f32 v[74:75], v[18:19], v[210:211], v[74:75]
; template <int OFF = 0, class V> __device__ __forceinline__ void st_wt16(void* p, V v) { static_assert(sizeof(V) == 16, ""); asm volatile("global_store_dwordx4 %0, %1, off offset:%2 sc1\n\ts_nop 1" :: "v"(p), "v"(v), "i"(OFF)); }
; template <int OFF = 0, class V> __device__ __forceinline__ void st_wt8(void* p, V v) { static_assert(sizeof(V) == 8, ""); asm volatile("global_store_dwordx2 %0, %1, off offset:%2 sc1\n\ts_nop 1" :: "v"(p), "v"(v), "i"(OFF)); }
; __device__ __forceinline__ unsigned pk2(float lo, float hi) { return pg8::cvt_pk_bf16(lo, hi); }
; __device__ __forceinline__ float bf_lo(unsigned w) { return __uint_as_float(w << 16); }
; __device__ __forceinline__ float bf_hi(unsigned w) { return __uint_as_float(w & 0xffff0000u); }
; __device__ __forceinline__ void resid_rows(bf16* __restrict__ XB, const bf16* __restrict__ Y, const float* __restrict__ PART, const float* __restrict__ g, float* __restrict__ RS, ...
;     ...
;         for (int j = 0; j < 16; ++j) { const int c = (lane + 64 * j) * 4;
;             f32x4 o; o.x = bf_lo(xr[j].x) + bf_lo(yr[j].x) * ry * gv[j].x; o.y = bf_hi(xr[j].x) + bf_hi(yr[j].x) * ry * gv[j].y; o.z = bf_lo(xr[j].y) + bf_lo(yr[j].y) * ry * gv[j].z; o.w = bf_hi(xr[j].y) + bf_hi(yr[j].y) * ry * gv[j].w;
;             ss += (o.x * o.x + o.y * o.y) + (o.z * o.z + o.w * o.w); ov[j] = o; am = fmaxf(fmaxf(am, fmaxf(fabsf(o.x), fabsf(o.y))), fmaxf(fabsf(o.z), fabsf(o.w)));
;             if (outf) st_wt16(outf + (size_t)m * DM + c, o); else { v2u ob; ob.x = pk2(o.x, o.y); ob.y = pk2(o.z, o.w); st_wt8(xrow + c, ob); } }
	v_max3_f32 v197, v197, |v74|, |v75|
	v_pk_fma_f32 v[202:203], v[74:75], v[74:75], v[202:203]
	v_cvt_pk_bf16_f32 v213, v74, v75
	v_lshlrev_b32_e32 v208, 16, v86
	v_and_b32_e32 v209, 0xffff0000, v86
	v_pk_mul_f32 v[208:209], v[198:199], v[208:209]
	v_lshlrev_b32_e32 v76, 16, v82
	v_and_b32_e32 v77, 0xffff0000, v82
	v_pk_fma_f32 v[76:77], v[20:21], v[208:209], v[76:77]
	v_max3_f32 v197, v197, |v76|, |v77|
	v_pk_fma_f32 v[202:203], v[76:77], v[76:77], v[202:203]
	v_cvt_pk_bf16_f32 v214, v76, v77
	v_lshlrev_b32_e32 v210, 16, v87
	v_and_b32_e32 v211, 0xffff0000, v87
	v_pk_mul_f32 v[210:211], v[198:199], v[210:211]
	v_lshlrev_b32_e32 v78, 16, v83
	v_and_b32_e32 v79, 0xffff0000, v83
	v_pk_fma_f32 v[78:79], v[22:23], v[210:211], v[78:79]
	v_max3_f32 v197, v197, |v78|, |v79|
	v_pk_fma_f32 v[202:203], v[78:79], v[78:79], v[202:203]
	v_cvt_pk_bf16_f32 v215, v78, v79
	global_store_dwordx4 v192, v[212:215], s[80:81] offset:2048 sc1 nt
	v_lshlrev_b32_e32 v208, 16, v92
	v_and_b32_e32 v209, 0xffff0000, v92
	v_pk_mul_f32 v[208:209], v[198:199], v[208:209]
	v_lshlrev_b32_e32 v80, 16, v88
	v_and_b32_e32 v81, 0xffff0000, v88
	v_pk_fma_f32 v[80:81], v[24:25], v[208:209], v[80:81]
	v_max3_f32 v197, v197, |v80|, |v81|
	v_pk_fma_f32 v[202:203], v[80:81], v[80:81], v[202:203]
	v_cvt_pk_bf16_f32 v246, v80, v81
	v_lshlrev_b32_e32 v210, 16, v93
	v_and_b32_e32 v211, 0xffff0000, v93
	v_pk_mul_f32 v[210:211], v[198:199], v[210:211]
	v_lshlrev_b32_e32 v82, 16, v89
	v_and_b32_e32 v83, 0xffff0000, v89
	v_pk_fma_f32 v[82:83], v[26:27], v[210:211], v[82:83]
	v_max3_f32 v197, v197, |v82|, |v83|
	v_pk_fma_f32 v[202:203], v[82:83], v[82:83], v[202:203]
	v_cvt_pk_bf16_f32 v247, v82, v83
	v_lshlrev_b32_e32 v208, 16, v94
	v_and_b32_e32 v209, 0xffff0000, v94
	v_pk_mul_f32 v[208:209], v[198:199], v[208:209]
	v_lshlrev_b32_e32 v84, 16, v90
	v_and_b32_e32 v85, 0xffff0000, v90
	v_pk_fma_f32 v[84:85], v[28:29], v[208:209], v[84:85]
	v_max3_f32 v197, v197, |v84|, |v85|
	v_pk_fma_f32 v[202:203], v[84:85], v[84:85], v[202:203]
	v_cvt_pk_bf16_f32 v248, v84, v85
	v_lshlrev_b32_e32 v210, 16, v95
	v_and_b32_e32 v211, 0xffff0000, v95
	v_pk_mul_f32 v[210:211], v[198:199], v[210:211]
	v_lshlrev_b32_e32 v86, 16, v91
	v_and_b32_e32 v87, 0xffff0000, v91
	v_pk_fma_f32 v[86:87], v[30:31], v[210:211], v[86:87]
	v_max3_f32 v197, v197, |v86|, |v87|
	v_pk_fma_f32 v[202:203], v[86:87], v[86:87], v[202:203]
	v_cvt_pk_bf16_f32 v249, v86, v87
	global_store_dwordx4 v192, v[246:249], s[80:81] offset:3072 sc1 nt
	v_lshlrev_b32_e32 v208, 16, v100
	v_and_b32_e32 v209, 0xffff0000, v100
	v_pk_mul_f32 v[208:209], v[198:199], v[208:209]
	v_lshlrev_b32_e32 v88, 16, v96
	v_and_b32_e32 v89, 0xffff0000, v96
	v_pk_fma_f32 v[88:89], v[32:33], v[208:209], v[88:89]
	v_max3_f32 v197, v197, |v88|, |v89|
	v_pk_fma_f32 v[202:203], v[88:89], v[88:89], v[202:203]
	v_cvt_pk_bf16_f32 v212, v88, v89
	v_lshlrev_b32_e32 v210, 16, v101
	v_and_b32_e32 v211, 0xffff0000, v101
	v_pk_mul_f32 v[210:211], v[198:199], v[210:211]
	v_lshlrev_b32_e32 v90, 16, v97
	v_and_b32_e32 v91, 0xffff0000, v97
	v_pk_fma_f32 v[90:91], v[34:35], v[210:211], v[90:91]
	v_max3_f32 v197, v197, |v90|, |v91|
	v_pk_fma_f32 v[202:203], v[90:91], v[90:91], v[202:203]
	v_cvt_pk_bf16_f32 v213, v90, v91
	v_lshlrev_b32_e32 v208, 16, v102
	v_and_b32_e32 v209, 0xffff0000, v102
	v_pk_mul_f32 v[208:209], v[198:199], v[208:209]
	v_lshlrev_b32_e32 v92, 16, v98
	v_and_b32_e32 v93, 0xffff0000, v98
	v_pk_fma_f32 v[92:93], v[36:37], v[208:209], v[92:93]
	v_max3_f32 v197, v197, |v92|, |v93|
	v_pk_fma_f32 v[202:203], v[92:93], v[92:93], v[202:203]
	v_cvt_pk_bf16_f32 v214, v92, v93
	v_lshlrev_b32_e32 v210, 16, v103
	v_and_b32_e32 v211, 0xffff0000, v103
	v_pk_mul_f32 v[210:211], v[198:199], v[210:211]
	v_lshlrev_b32_e32 v94, 16, v99
	v_and_b32_e32 v95, 0xffff0000, v99
	v_pk_fma_f32 v[94:95], v[38:39], v[210:211], v[94:95]
	v_max3_f32 v197, v197, |v94|, |v95|
	v_pk_fma_f32 v[202:203], v[94:95], v[94:95], v[202:203]
	v_cvt_pk_bf16_f32 v215, v94, v95
	global_store_dwordx4 v193, v[212:215], s[80:81] offset:0 sc1 nt
	v_lshlrev_b32_e32 v208, 16, v108
	v_and_b32_e32 v209, 0xffff0000, v108
	v_pk_mul_f32 v[208:209], v[198:199], v[208:209]
	v_lshlrev_b32_e32 v96, 16, v104
	v_and_b32_e32 v97, 0xffff0000, v104
	v_pk_fma_f32 v[96:97], v[40:41], v[208:209], v[96:97]
	v_max3_f32 v197, v197, |v96|, |v97|
	v_pk_fma_f32 v[202:203], v[96:97], v[96:97], v[202:203]
	v_cvt_pk_bf16_f32 v246, v96, v97
	v_lshlrev_b32_e32 v210, 16, v109
	v_and_b32_e32 v211, 0xffff0000, v109
	v_pk_mul_f32 v[210:211], v[198:199], v[210:211]
	v_lshlrev_b32_e32 v98, 16, v105
	v_and_b32_e32 v99, 0xffff0000, v105
	v_pk_fma_f32 v[98:99], v[42:43], v[210:211], v[98:99]
	v_max3_f32 v197, v197, |v98|, |v99|
	v_pk_fma_f32 v[202:203], v[98:99], v[98:99], v[202:203]
	v_cvt_pk_bf16_f32 v247, v98, v99
	v_lshlrev_b32_e32 v208, 16, v110
	v_and_b32_e32 v209, 0xffff0000, v110
	v_pk_mul_f32 v[208:209], v[198:199], v[208:209]
	v_lshlrev_b32_e32 v100, 16, v106
	v_and_b32_e32 v101, 0xffff0000, v106
	v_pk_fma_f32 v[100:101], v[44:45], v[208:209], v[100:101]
	v_max3_f32 v197, v197, |v100|, |v101|
	v_pk_fma_f32 v[202:203], v[100:101], v[100:101], v[202:203]
	v_cvt_pk_bf16_f32 v248, v100, v101
	v_lshlrev_b32_e32 v210, 16, v111
	v_and_b32_e32 v211, 0xffff0000, v111
	v_pk_mul_f32 v[210:211], v[198:199], v[210:211]
	v_lshlrev_b32_e32 v102, 16, v107
	v_and_b32_e32 v103, 0xffff0000, v107
	v_pk_fma_f32 v[102:103], v[46:47], v[210:211], v[102:103]
	v_max3_f32 v197, v197, |v102|, |v103|
	v_pk_fma_f32 v[202:203], v[102:103], v[102:103], v[202:203]
	v_cvt_pk_bf16_f32 v249, v102, v103
	global_store_dwordx4 v193, v[246:249], s[80:81] offset:1024 sc1 nt
; template <int OFF = 0, class V> __device__ __forceinline__ void st_wt16(void* p, V v) { static_assert(sizeof(V) == 16, ""); asm volatile("global_store_dwordx4 %0, %1, off offset:%2 sc1\n\ts_nop 1" :: "v"(p), "v"(v), "i"(OFF)); }
; template <int OFF = 0, class V> __device__ __forceinline__ void st_wt8(void* p, V v) { static_assert(sizeof(V) == 8, ""); asm volatile("global_store_dwordx2 %0, %1, off offset:%2 sc1\n\ts_nop 1" :: "v"(p), "v"(v), "i"(OFF)); }
; __device__ __forceinline__ void st_wt4(void* p, unsigned v) { asm volatile("global_store_dword %0, %1, off sc1\n\ts_nop 1" :: "v"(p), "v"(v)); }
; __device__ __forceinline__ unsigned pk2(float lo, float hi) { return pg8::cvt_pk_bf16(lo, hi); }
; __device__ __forceinline__ float bf_lo(unsigned w) { return __uint_as_float(w << 16); }
; __device__ __forceinline__ float bf_hi(unsigned w) { return __uint_as_float(w & 0xffff0000u); }
; __device__ __forceinline__ void resid_rows(bf16* __restrict__ XB, const bf16* __restrict__ Y, const float* __restrict__ PART, const float* __restrict__ g, float* __restrict__ RS, ...
;     ...
;         for (int j = 0; j < 16; ++j) { const int c = (lane + 64 * j) * 4;
;             f32x4 o; o.x = bf_lo(xr[j].x) + bf_lo(yr[j].x) * ry * gv[j].x; o.y = bf_hi(xr[j].x) + bf_hi(yr[j].x) * ry * gv[j].y; o.z = bf_lo(xr[j].y) + bf_lo(yr[j].y) * ry * gv[j].z; o.w = bf_hi(xr[j].y) + bf_hi(yr[j].y) * ry * gv[j].w;
;             ss += (o.x * o.x + o.y * o.y) + (o.z * o.z + o.w * o.w); ov[j] = o; am = fmaxf(fmaxf(am, fmaxf(fabsf(o.x), fabsf(o.y))), fmaxf(fabsf(o.z), fabsf(o.w)));
;             if (outf) st_wt16(outf + (size_t)m * DM + c, o); else { v2u ob; ob.x = pk2(o.x, o.y); ob.y = pk2(o.z, o.w); st_wt8(xrow + c, ob); } }
;         if (XQ) {
;             am = fmaxf(wave_max(am), 1e-20f); const float qs = 127.0f / am;
; #pragma unroll
;             for (int j = 0; j < 16; ++j) { const int q0 = (int)rintf(ov[j].x * qs), q1 = (int)rintf(ov[j].y * qs), q2 = (int)rintf(ov[j].z * qs), q3 = (int)rintf(ov[j].w * qs);
;                 st_wt4(XQ + (size_t)m * (DM / 4) + lane + 64 * j, ((unsigned)q0 & 255u) | (((unsigned)q1 & 255u) << 8) | (((unsigned)q2 & 255u) << 16) | ((unsigned)q3 << 24)); }
;             if (lane == 0) AS[m] = am * (1.0f / 127.0f); }
;         ss = wave_sum(ss);
	v_lshlrev_b32_e32 v208, 16, v116
	v_and_b32_e32 v209, 0xffff0000, v116
	v_pk_mul_f32 v[208:209], v[198:199], v[208:209]
	v_lshlrev_b32_e32 v104, 16, v112
	v_and_b32_e32 v105, 0xffff0000, v112
	v_pk_fma_f32 v[104:105], v[48:49], v[208:209], v[104:105]
	v_max3_f32 v197, v197, |v104|, |v105|
	v_pk_fma_f32 v[202:203], v[104:105], v[104:105], v[202:203]
	v_cvt_pk_bf16_f32 v212, v104, v105
	v_lshlrev_b32_e32 v210, 16, v117
	v_and_b32_e32 v211, 0xffff0000, v117
	v_pk_mul_f32 v[210:211], v[198:199], v[210:211]
	v_lshlrev_b32_e32 v106, 16, v113
	v_and_b32_e32 v107, 0xffff0000, v113
	v_pk_fma_f32 v[106:107], v[50:51], v[210:211], v[106:107]
	v_max3_f32 v197, v197, |v106|, |v107|
	v_pk_fma_f32 v[202:203], v[106:107], v[106:107], v[202:203]
	v_cvt_pk_bf16_f32 v213, v106, v107
	v_lshlrev_b32_e32 v208, 16, v118
	v_and_b32_e32 v209, 0xffff0000, v118
	v_pk_mul_f32 v[208:209], v[198:199], v[208:209]
	v_lshlrev_b32_e32 v108, 16, v114
	v_and_b32_e32 v109, 0xffff0000, v114
	v_pk_fma_f32 v[108:109], v[52:53], v[208:209], v[108:109]
	v_max3_f32 v197, v197, |v108|, |v109|
	v_pk_fma_f32 v[202:203], v[108:109], v[108:109], v[202:203]
	v_cvt_pk_bf16_f32 v214, v108, v109
	v_lshlrev_b32_e32 v210, 16, v119
	v_and_b32_e32 v211, 0xffff0000, v119
	v_pk_mul_f32 v[210:211], v[198:199], v[210:211]
	v_lshlrev_b32_e32 v110, 16, v115
	v_and_b32_e32 v111, 0xffff0000, v115
	v_pk_fma_f32 v[110:111], v[54:55], v[210:211], v[110:111]
	v_max3_f32 v197, v197, |v110|, |v111|
	v_pk_fma_f32 v[202:203], v[110:111], v[110:111], v[202:203]
	v_cvt_pk_bf16_f32 v215, v110, v111
	global_store_dwordx4 v193, v[212:215], s[80:81] offset:2048 sc1 nt
	v_lshlrev_b32_e32 v208, 16, v124
	v_and_b32_e32 v209, 0xffff0000, v124
	v_pk_mul_f32 v[208:209], v[198:199], v[208:209]
	v_lshlrev_b32_e32 v112, 16, v120
	v_and_b32_e32 v113, 0xffff0000, v120
	v_pk_fma_f32 v[112:113], v[56:57], v[208:209], v[112:113]
	v_max3_f32 v197, v197, |v112|, |v113|
	v_pk_fma_f32 v[202:203], v[112:113], v[112:113], v[202:203]
	v_cvt_pk_bf16_f32 v246, v112, v113
	v_lshlrev_b32_e32 v210, 16, v125
	v_and_b32_e32 v211, 0xffff0000, v125
	v_pk_mul_f32 v[210:211], v[198:199], v[210:211]
	v_lshlrev_b32_e32 v114, 16, v121
	v_and_b32_e32 v115, 0xffff0000, v121
	v_pk_fma_f32 v[114:115], v[58:59], v[210:211], v[114:115]
	v_max3_f32 v197, v197, |v114|, |v115|
	v_pk_fma_f32 v[202:203], v[114:115], v[114:115], v[202:203]
	v_cvt_pk_bf16_f32 v247, v114, v115
	v_lshlrev_b32_e32 v208, 16, v126
	v_and_b32_e32 v209, 0xffff0000, v126
	v_pk_mul_f32 v[208:209], v[198:199], v[208:209]
	v_lshlrev_b32_e32 v116, 16, v122
	v_and_b32_e32 v117, 0xffff0000, v122
	v_pk_fma_f32 v[116:117], v[60:61], v[208:209], v[116:117]
	v_max3_f32 v197, v197, |v116|, |v117|
	v_pk_fma_f32 v[202:203], v[116:117], v[116:117], v[202:203]
	v_cvt_pk_bf16_f32 v248, v116, v117
	v_lshlrev_b32_e32 v210, 16, v127
	v_and_b32_e32 v211, 0xffff0000, v127
	v_pk_mul_f32 v[210:211], v[198:199], v[210:211]
	v_lshlrev_b32_e32 v118, 16, v123
	v_and_b32_e32 v119, 0xffff0000, v123
	v_pk_fma_f32 v[118:119], v[62:63], v[210:211], v[118:119]
	v_max3_f32 v197, v197, |v118|, |v119|
	v_pk_fma_f32 v[202:203], v[118:119], v[118:119], v[202:203]
	v_cvt_pk_bf16_f32 v249, v118, v119
	global_store_dwordx4 v193, v[246:249], s[80:81] offset:3072 sc1 nt
	v_add_f32_e32 v202, v202, v203
	s_waitcnt vmcnt(24)
	ds_swizzle_b32 v238, v197 offset:swizzle(SWAP,1)
	ds_swizzle_b32 v241, v202 offset:swizzle(SWAP,1)
	ds_swizzle_b32 v252, v251 offset:swizzle(SWAP,1)
	s_nop 0
	s_waitcnt lgkmcnt(0)
	v_max_f32_e32 v197, v197, v238
	v_add_f32_e32 v202, v202, v241
	v_add_f32_e32 v251, v251, v252
	ds_swizzle_b32 v238, v197 offset:swizzle(SWAP,2)
	ds_swizzle_b32 v241, v202 offset:swizzle(SWAP,2)
	ds_swizzle_b32 v252, v251 offset:swizzle(SWAP,2)
	s_nop 0
	s_waitcnt lgkmcnt(0)
	v_max_f32_e32 v197, v197, v238
	v_add_f32_e32 v202, v202, v241
	v_add_f32_e32 v251, v251, v252
	ds_swizzle_b32 v238, v197 offset:swizzle(SWAP,4)
	ds_swizzle_b32 v241, v202 offset:swizzle(SWAP,4)
	ds_swizzle_b32 v252, v251 offset:swizzle(SWAP,4)
	s_nop 0
	s_waitcnt lgkmcnt(0)
	v_max_f32_e32 v197, v197, v238
	v_add_f32_e32 v202, v202, v241
	v_add_f32_e32 v251, v251, v252
	ds_swizzle_b32 v238, v197 offset:swizzle(SWAP,8)
	ds_swizzle_b32 v241, v202 offset:swizzle(SWAP,8)
	ds_swizzle_b32 v252, v251 offset:swizzle(SWAP,8)
	s_nop 0
	s_waitcnt lgkmcnt(0)
	v_max_f32_e32 v197, v197, v238
	v_add_f32_e32 v202, v202, v241
	v_add_f32_e32 v251, v251, v252
	ds_swizzle_b32 v238, v197 offset:swizzle(SWAP,16)
	ds_swizzle_b32 v241, v202 offset:swizzle(SWAP,16)
	ds_swizzle_b32 v252, v251 offset:swizzle(SWAP,16)
	s_nop 0
	s_waitcnt lgkmcnt(0)
; template <int OFF = 0, class V> __device__ __forceinline__ void st_wt16(void* p, V v) { static_assert(sizeof(V) == 16, ""); asm volatile("global_store_dwordx4 %0, %1, off offset:%2 sc1\n\ts_nop 1" :: "v"(p), "v"(v), "i"(OFF)); }
; template <int OFF = 0, class V> __device__ __forceinline__ void st_wt8(void* p, V v) { static_assert(sizeof(V) == 8, ""); asm volatile("global_store_dwordx2 %0, %1, off offset:%2 sc1\n\ts_nop 1" :: "v"(p), "v"(v), "i"(OFF)); }
; __device__ __forceinline__ void st_wt4(void* p, unsigned v) { asm volatile("global_store_dword %0, %1, off sc1\n\ts_nop 1" :: "v"(p), "v"(v)); }
; __device__ __forceinline__ unsigned pk2(float lo, float hi) { return pg8::cvt_pk_bf16(lo, hi); }
; __device__ __forceinline__ float bf_lo(unsigned w) { return __uint_as_float(w << 16); }
; __device__ __forceinline__ void resid_rows(bf16* __restrict__ XB, const bf16* __restrict__ Y, const float* __restrict__ PART, const float* __restrict__ g, float* __restrict__ RS, ...
;     ...
;         const float ry = 1.0f / sqrtf(wave_sum(pv) * (1.0f / DM) + EPS);
;         float ss = 0.f, am = 0.f; f32x4 ov[16];
; #pragma unroll
;         for (int j = 0; j < 16; ++j) { const int c = (lane + 64 * j) * 4;
;             f32x4 o; o.x = bf_lo(xr[j].x) + bf_lo(yr[j].x) * ry * gv[j].x; o.y = bf_hi(xr[j].x) + bf_hi(yr[j].x) * ry * gv[j].y; o.z = bf_lo(xr[j].y) + bf_lo(yr[j].y) * ry * gv[j].z; o.w = bf_hi(xr[j].y) + bf_hi(yr[j].y) * ry * gv[j].w;
;             ss += (o.x * o.x + o.y * o.y) + (o.z * o.z + o.w * o.w); ov[j] = o; am = fmaxf(fmaxf(am, fmaxf(fabsf(o.x), fabsf(o.y))), fmaxf(fabsf(o.z), fabsf(o.w)));
;             if (outf) st_wt16(outf + (size_t)m * DM + c, o); else { v2u ob; ob.x = pk2(o.x, o.y); ob.y = pk2(o.z, o.w); st_wt8(xrow + c, ob); } }
;         if (XQ) {
;             am = fmaxf(wave_max(am), 1e-20f); const float qs = 127.0f / am;
; #pragma unroll
;             for (int j = 0; j < 16; ++j) { const int q0 = (int)rintf(ov[j].x * qs), q1 = (int)rintf(ov[j].y * qs), q2 = (int)rintf(ov[j].z * qs), q3 = (int)rintf(ov[j].w * qs);
;                 st_wt4(XQ + (size_t)m * (DM / 4) + lane + 64 * j, ((unsigned)q0 & 255u) | (((unsigned)q1 & 255u) << 8) | (((unsigned)q2 & 255u) << 16) | ((unsigned)q3 << 24)); }
;             if (lane == 0) AS[m] = am * (1.0f / 127.0f); }
;         ss = wave_sum(ss);
;         if (lane == 0) RS[m] = 1.0f / sqrtf(ss * (1.0f / DM) + EPS);
	v_max_f32_e32 v197, v197, v238
	v_add_f32_e32 v202, v202, v241
	v_add_f32_e32 v251, v251, v252
	v_mov_b32_e32 v238, v197
	v_mov_b32_e32 v241, v202
	v_mov_b32_e32 v252, v251
	s_nop 1
	v_permlane32_swap_b32_e32 v197, v238
	v_permlane32_swap_b32_e32 v202, v241
	v_permlane32_swap_b32_e32 v251, v252
	v_max3_f32 v197, v197, v238, s58
	v_add_f32_e32 v202, v202, v241
	v_add_f32_e32 v251, v251, v252
	v_div_scale_f32 v212, s[0:1], v197, v197, s57
	v_rcp_f32_e32 v213, v212
	s_nop 0
	v_fma_f32 v214, -v212, v213, 1.0
	v_fmac_f32_e32 v213, v214, v213
	v_div_scale_f32 v214, vcc, s57, v197, s57
	v_mul_f32_e32 v215, v214, v213
	v_fma_f32 v246, -v212, v215, v214
	v_fmac_f32_e32 v215, v246, v213
	v_fma_f32 v214, -v212, v215, v214
	v_div_fmas_f32 v214, v214, v213, v215
	v_div_fixup_f32 v204, v214, v197, s57
	v_mov_b32_e32 v205, v204
	v_fmamk_f32 v212, v251, 0x39800000, v216
	v_mul_f32_e32 v213, 0x4f800000, v212
	v_cmp_gt_f32_e32 vcc, s59, v212
	s_nop 1
	v_cndmask_b32_e32 v214, v212, v213, vcc
	v_sqrt_f32_e32 v215, v214
	s_nop 0
	s_nop 0
	v_add_u32_e32 v246, -1, v215
	v_fma_f32 v247, -v246, v215, v214
	v_cmp_ge_f32_e64 s[62:63], 0, v247
	v_add_u32_e32 v247, 1, v215
	v_fma_f32 v248, -v247, v215, v214
	v_cndmask_b32_e64 v246, v215, v246, s[62:63]
	v_cmp_lt_f32_e64 s[62:63], 0, v248
	s_nop 1
	v_cndmask_b32_e64 v246, v246, v247, s[62:63]
	v_mul_f32_e32 v247, 0x37800000, v246
	v_cndmask_b32_e32 v246, v246, v247, vcc
	v_cmp_class_f32_e32 vcc, v214, v239
	s_nop 1
	v_cndmask_b32_e32 v248, v246, v214, vcc
	v_div_scale_f32 v249, s[0:1], v248, v248, 1.0
	v_rcp_f32_e32 v212, v249
	s_nop 0
	v_fma_f32 v213, -v249, v212, 1.0
	v_fmac_f32_e32 v212, v213, v212
	v_div_scale_f32 v213, vcc, 1.0, v248, 1.0
	v_mul_f32_e32 v214, v213, v212
	v_fma_f32 v215, -v249, v214, v213
	v_fmac_f32_e32 v214, v215, v212
	v_fma_f32 v213, -v249, v214, v213
	v_div_fmas_f32 v213, v213, v212, v214
	v_div_fixup_f32 v200, v213, v248, 1.0
	v_fmamk_f32 v212, v202, 0x39800000, v216
	v_mul_f32_e32 v213, 0x4f800000, v212
	v_cmp_gt_f32_e32 vcc, s59, v212
	s_nop 1
	v_cndmask_b32_e32 v214, v212, v213, vcc
	v_sqrt_f32_e32 v215, v214
	s_nop 0
	s_nop 0
	v_add_u32_e32 v246, -1, v215
	v_fma_f32 v247, -v246, v215, v214
	v_cmp_ge_f32_e64 s[62:63], 0, v247
	v_add_u32_e32 v247, 1, v215
	v_fma_f32 v248, -v247, v215, v214
	v_cndmask_b32_e64 v246, v215, v246, s[62:63]
	v_cmp_lt_f32_e64 s[62:63], 0, v248
	s_nop 1
	v_cndmask_b32_e64 v246, v246, v247, s[62:63]
	v_mul_f32_e32 v247, 0x37800000, v246
	v_cndmask_b32_e32 v246, v246, v247, vcc
	v_cmp_class_f32_e32 vcc, v214, v239
	s_nop 1
	v_cndmask_b32_e32 v248, v246, v214, vcc
	v_div_scale_f32 v249, s[0:1], v248, v248, 1.0
	v_rcp_f32_e32 v212, v249
	s_nop 0
	v_fma_f32 v213, -v249, v212, 1.0
	v_fmac_f32_e32 v212, v213, v212
	v_div_scale_f32 v213, vcc, 1.0, v248, 1.0
	v_mul_f32_e32 v214, v213, v212
	v_fma_f32 v215, -v249, v214, v213
	v_fmac_f32_e32 v214, v215, v212
	v_fma_f32 v213, -v249, v214, v213
	v_div_fmas_f32 v213, v213, v212, v214
	v_div_fixup_f32 v241, v213, v248, 1.0
	v_mul_f32_e32 v238, 0x3c010204, v197
	v_pk_mul_f32 v[208:209], v[220:221], v[204:205]
	v_pk_mul_f32 v[210:211], v[222:223], v[204:205]
	v_pk_add_f32 v[208:209], v[208:209], v[206:207]
	v_pk_add_f32 v[210:211], v[210:211], v[206:207]
	v_perm_b32 v208, v209, v208, s60
	v_perm_b32 v210, v211, v210, s61
	v_or_b32_e32 v212, v208, v210
	v_pk_mul_f32 v[208:209], v[224:225], v[204:205]
	v_pk_mul_f32 v[210:211], v[226:227], v[204:205]
	v_pk_add_f32 v[208:209], v[208:209], v[206:207]
	v_pk_add_f32 v[210:211], v[210:211], v[206:207]
	v_perm_b32 v208, v209, v208, s60
	v_perm_b32 v210, v211, v210, s61
	v_or_b32_e32 v213, v208, v210
	global_store_dwordx2 v194, v[212:213], s[82:83] offset:0 sc1
	v_pk_mul_f32 v[208:209], v[64:65], v[204:205]
	v_pk_mul_f32 v[210:211], v[66:67], v[204:205]
	v_pk_add_f32 v[208:209], v[208:209], v[206:207]
	v_pk_add_f32 v[210:211], v[210:211], v[206:207]
	v_perm_b32 v208, v209, v208, s60
	v_perm_b32 v210, v211, v210, s61
	v_or_b32_e32 v246, v208, v210
	v_pk_mul_f32 v[208:209], v[68:69], v[204:205]
	v_pk_mul_f32 v[210:211], v[70:71], v[204:205]
	v_pk_add_f32 v[208:209], v[208:209], v[206:207]
	v_pk_add_f32 v[210:211], v[210:211], v[206:207]
	v_perm_b32 v208, v209, v208, s60
; __device__ __forceinline__ void st_wt4(void* p, unsigned v) { asm volatile("global_store_dword %0, %1, off sc1\n\ts_nop 1" :: "v"(p), "v"(v)); }
; __device__ __forceinline__ void resid_rows(bf16* __restrict__ XB, const bf16* __restrict__ Y, const float* __restrict__ PART, const float* __restrict__ g, float* __restrict__ RS, ...
;     ...
;             for (int j = 0; j < 16; ++j) { const int q0 = (int)rintf(ov[j].x * qs), q1 = (int)rintf(ov[j].y * qs), q2 = (int)rintf(ov[j].z * qs), q3 = (int)rintf(ov[j].w * qs);
;                 st_wt4(XQ + (size_t)m * (DM / 4) + lane + 64 * j, ((unsigned)q0 & 255u) | (((unsigned)q1 & 255u) << 8) | (((unsigned)q2 & 255u) << 16) | ((unsigned)q3 << 24)); }
;             if (lane == 0) AS[m] = am * (1.0f / 127.0f); }
;         ss = wave_sum(ss);
;         if (lane == 0) RS[m] = 1.0f / sqrtf(ss * (1.0f / DM) + EPS);
	v_perm_b32 v210, v211, v210, s61
	v_or_b32_e32 v247, v208, v210
	global_store_dwordx2 v194, v[246:247], s[82:83] offset:512 sc1
	v_pk_mul_f32 v[208:209], v[72:73], v[204:205]
	v_pk_mul_f32 v[210:211], v[74:75], v[204:205]
	v_pk_add_f32 v[208:209], v[208:209], v[206:207]
	v_pk_add_f32 v[210:211], v[210:211], v[206:207]
	v_perm_b32 v208, v209, v208, s60
	v_perm_b32 v210, v211, v210, s61
	v_or_b32_e32 v212, v208, v210
	v_pk_mul_f32 v[208:209], v[76:77], v[204:205]
	v_pk_mul_f32 v[210:211], v[78:79], v[204:205]
	v_pk_add_f32 v[208:209], v[208:209], v[206:207]
	v_pk_add_f32 v[210:211], v[210:211], v[206:207]
	v_perm_b32 v208, v209, v208, s60
	v_perm_b32 v210, v211, v210, s61
	v_or_b32_e32 v213, v208, v210
	global_store_dwordx2 v194, v[212:213], s[82:83] offset:1024 sc1
	v_pk_mul_f32 v[208:209], v[80:81], v[204:205]
	v_pk_mul_f32 v[210:211], v[82:83], v[204:205]
	v_pk_add_f32 v[208:209], v[208:209], v[206:207]
	v_pk_add_f32 v[210:211], v[210:211], v[206:207]
	v_perm_b32 v208, v209, v208, s60
	v_perm_b32 v210, v211, v210, s61
	v_or_b32_e32 v246, v208, v210
	v_pk_mul_f32 v[208:209], v[84:85], v[204:205]
	v_pk_mul_f32 v[210:211], v[86:87], v[204:205]
	v_pk_add_f32 v[208:209], v[208:209], v[206:207]
	v_pk_add_f32 v[210:211], v[210:211], v[206:207]
	v_perm_b32 v208, v209, v208, s60
	v_perm_b32 v210, v211, v210, s61
	v_or_b32_e32 v247, v208, v210
	global_store_dwordx2 v194, v[246:247], s[82:83] offset:1536 sc1
	v_pk_mul_f32 v[208:209], v[88:89], v[204:205]
	v_pk_mul_f32 v[210:211], v[90:91], v[204:205]
	v_pk_add_f32 v[208:209], v[208:209], v[206:207]
	v_pk_add_f32 v[210:211], v[210:211], v[206:207]
	v_perm_b32 v208, v209, v208, s60
	v_perm_b32 v210, v211, v210, s61
	v_or_b32_e32 v212, v208, v210
	v_pk_mul_f32 v[208:209], v[92:93], v[204:205]
	v_pk_mul_f32 v[210:211], v[94:95], v[204:205]
	v_pk_add_f32 v[208:209], v[208:209], v[206:207]
	v_pk_add_f32 v[210:211], v[210:211], v[206:207]
	v_perm_b32 v208, v209, v208, s60
	v_perm_b32 v210, v211, v210, s61
	v_or_b32_e32 v213, v208, v210
	global_store_dwordx2 v194, v[212:213], s[82:83] offset:2048 sc1
	v_pk_mul_f32 v[208:209], v[96:97], v[204:205]
	v_pk_mul_f32 v[210:211], v[98:99], v[204:205]
	v_pk_add_f32 v[208:209], v[208:209], v[206:207]
	v_pk_add_f32 v[210:211], v[210:211], v[206:207]
	v_perm_b32 v208, v209, v208, s60
	v_perm_b32 v210, v211, v210, s61
	v_or_b32_e32 v246, v208, v210
	v_pk_mul_f32 v[208:209], v[100:101], v[204:205]
	v_pk_mul_f32 v[210:211], v[102:103], v[204:205]
	v_pk_add_f32 v[208:209], v[208:209], v[206:207]
	v_pk_add_f32 v[210:211], v[210:211], v[206:207]
	v_perm_b32 v208, v209, v208, s60
	v_perm_b32 v210, v211, v210, s61
	v_or_b32_e32 v247, v208, v210
	global_store_dwordx2 v194, v[246:247], s[82:83] offset:2560 sc1
	v_pk_mul_f32 v[208:209], v[104:105], v[204:205]
	v_pk_mul_f32 v[210:211], v[106:107], v[204:205]
	v_pk_add_f32 v[208:209], v[208:209], v[206:207]
	v_pk_add_f32 v[210:211], v[210:211], v[206:207]
	v_perm_b32 v208, v209, v208, s60
	v_perm_b32 v210, v211, v210, s61
	v_or_b32_e32 v212, v208, v210
	v_pk_mul_f32 v[208:209], v[108:109], v[204:205]
	v_pk_mul_f32 v[210:211], v[110:111], v[204:205]
	v_pk_add_f32 v[208:209], v[208:209], v[206:207]
	v_pk_add_f32 v[210:211], v[210:211], v[206:207]
	v_perm_b32 v208, v209, v208, s60
	v_perm_b32 v210, v211, v210, s61
	v_or_b32_e32 v213, v208, v210
	global_store_dwordx2 v194, v[212:213], s[82:83] offset:3072 sc1
	v_pk_mul_f32 v[208:209], v[112:113], v[204:205]
	v_pk_mul_f32 v[210:211], v[114:115], v[204:205]
	v_pk_add_f32 v[208:209], v[208:209], v[206:207]
	v_pk_add_f32 v[210:211], v[210:211], v[206:207]
	v_perm_b32 v208, v209, v208, s60
	v_perm_b32 v210, v211, v210, s61
	v_or_b32_e32 v246, v208, v210
	v_pk_mul_f32 v[208:209], v[116:117], v[204:205]
	v_pk_mul_f32 v[210:211], v[118:119], v[204:205]
	v_pk_add_f32 v[208:209], v[208:209], v[206:207]
	v_pk_add_f32 v[210:211], v[210:211], v[206:207]
	v_perm_b32 v208, v209, v208, s60
	v_perm_b32 v210, v211, v210, s61
	v_or_b32_e32 v247, v208, v210
	global_store_dwordx2 v194, v[246:247], s[82:83] offset:3584 sc1
	s_mov_b64 exec, 1
	global_store_dword v196, v238, s[86:87]
	global_store_dword v196, v241, s[84:85]
	s_mov_b64 exec, -1
	s_mov_b32 s8, s9
	s_cmp_eq_u32 s16, 0
	s_cbranch_scc1 .LBB0_818

; template <int OFF = 0, class V> __device__ __forceinline__ void st_wt16(void* p, V v) { static_assert(sizeof(V) == 16, ""); asm volatile("global_store_dwordx4 %0, %1, off offset:%2 sc1\n\ts_nop 1" :: "v"(p), "v"(v), "i"(OFF)); }
; template <int OFF = 0, class V> __device__ __forceinline__ void st_wt8(void* p, V v) { static_assert(sizeof(V) == 8, ""); asm volatile("global_store_dwordx2 %0, %1, off offset:%2 sc1\n\ts_nop 1" :: "v"(p), "v"(v), "i"(OFF)); }
; __device__ __forceinline__ unsigned pk2(float lo, float hi) { return pg8::cvt_pk_bf16(lo, hi); }
; __device__ __forceinline__ float bf_lo(unsigned w) { return __uint_as_float(w << 16); }
; __device__ __forceinline__ float bf_hi(unsigned w) { return __uint_as_float(w & 0xffff0000u); }
; __device__ __forceinline__ void resid_rows(bf16* __restrict__ XB, const bf16* __restrict__ Y, const float* __restrict__ PART, const float* __restrict__ g, float* __restrict__ RS, ...
;     ...
;     for (int m = gw; m < MTOK; m += NGW) {
;         const float pv = PART[(size_t)m * 64 + lane];
;         bf16* xrow = XB + (size_t)m * DM; const bf16* yrow = Y + (size_t)m * DM;
;         v2u xr[16], yr[16];
; #pragma unroll
;         for (int j = 0; j < 16; ++j) { xr[j] = *(const v2u*)(xrow + (lane + 64 * j) * 4); yr[j] = *(const v2u*)(yrow + (lane + 64 * j) * 4); }
;         const float ry = 1.0f / sqrtf(wave_sum(pv) * (1.0f / DM) + EPS);
;         float ss = 0.f, am = 0.f; f32x4 ov[16];
; #pragma unroll
;         for (int j = 0; j < 16; ++j) { const int c = (lane + 64 * j) * 4;
;             f32x4 o; o.x = bf_lo(xr[j].x) + bf_lo(yr[j].x) * ry * gv[j].x; o.y = bf_hi(xr[j].x) + bf_hi(yr[j].x) * ry * gv[j].y; o.z = bf_lo(xr[j].y) + bf_lo(yr[j].y) * ry * gv[j].z; o.w = bf_hi(xr[j].y) + bf_hi(yr[j].y) * ry * gv[j].w;
;             ss += (o.x * o.x + o.y * o.y) + (o.z * o.z + o.w * o.w); ov[j] = o; am = fmaxf(fmaxf(am, fmaxf(fabsf(o.x), fabsf(o.y))), fmaxf(fabsf(o.z), fabsf(o.w)));
;             if (outf) st_wt16(outf + (size_t)m * DM + c, o); else { v2u ob; ob.x = pk2(o.x, o.y); ob.y = pk2(o.z, o.w); st_wt8(xrow + c, ob); } }
.Lr1_B_go:
	v_mov_b32_e32 v198, v200
	v_mov_b32_e32 v199, v200
	s_lshl_b32 s0, s8, 13
	s_add_u32 s80, s76, s0
	s_addc_u32 s81, s77, 0
	s_lshl_b32 s0, s8, 12
	s_add_u32 s82, s78, s0
	s_addc_u32 s83, s79, 0
	s_lshl_b32 s0, s8, 2
	s_add_u32 s84, s18, s0
	s_addc_u32 s85, s19, 0
	s_add_u32 s84, s84, 0x100000
	s_addc_u32 s85, s85, 0
	s_add_u32 s86, s84, 0x10000
	s_addc_u32 s87, s85, 0
	s_add_i32 s9, s8, s14
	s_cmpk_lt_i32 s9, 0x2000
	s_cselect_b32 s16, 1, 0
	v_mov_b32_e32 v250, 1.0
	s_cbranch_scc0 .Lr1_B_noissue
	s_lshl_b32 s0, s9, 8
	s_add_u32 s4, s18, s0
	s_addc_u32 s5, s19, 0
	s_add_u32 s4, s4, 0x400000
	s_addc_u32 s5, s5, 0
	global_load_dword v250, v195, s[4:5]
	s_lshl_b32 s0, s9, 13
	s_add_u32 s24, s76, s0
	s_addc_u32 s25, s77, 0
	s_add_u32 s26, s24, 0x11000000
	s_addc_u32 s27, s25, 0
	global_load_dwordx4 v[64:67], v192, s[24:25] offset:0 nt
	global_load_dwordx4 v[68:71], v192, s[26:27] offset:0 nt
	global_load_dwordx4 v[72:75], v192, s[24:25] offset:1024 nt
	global_load_dwordx4 v[76:79], v192, s[26:27] offset:1024 nt
	global_load_dwordx4 v[80:83], v192, s[24:25] offset:2048 nt
	global_load_dwordx4 v[84:87], v192, s[26:27] offset:2048 nt
	global_load_dwordx4 v[88:91], v192, s[24:25] offset:3072 nt
	global_load_dwordx4 v[92:95], v192, s[26:27] offset:3072 nt
	global_load_dwordx4 v[96:99], v193, s[24:25] offset:0 nt
	global_load_dwordx4 v[100:103], v193, s[26:27] offset:0 nt
	global_load_dwordx4 v[104:107], v193, s[24:25] offset:1024 nt
	global_load_dwordx4 v[108:111], v193, s[26:27] offset:1024 nt
	global_load_dwordx4 v[112:115], v193, s[24:25] offset:2048 nt
	global_load_dwordx4 v[116:119], v193, s[26:27] offset:2048 nt
	global_load_dwordx4 v[120:123], v193, s[24:25] offset:3072 nt
	global_load_dwordx4 v[124:127], v193, s[26:27] offset:3072 nt
.Lr1_B_noissue:
	v_mov_b32_e32 v197, 0
	v_mov_b32_e32 v202, 0
	v_mov_b32_e32 v203, 0
	v_lshlrev_b32_e32 v208, 16, v132
	v_and_b32_e32 v209, 0xffff0000, v132
	v_pk_mul_f32 v[208:209], v[198:199], v[208:209]
	v_lshlrev_b32_e32 v220, 16, v128
	v_and_b32_e32 v221, 0xffff0000, v128
	v_pk_fma_f32 v[220:221], v[0:1], v[208:209], v[220:221]
	v_max3_f32 v197, v197, |v220|, |v221|
	v_pk_fma_f32 v[202:203], v[220:221], v[220:221], v[202:203]
	v_cvt_pk_bf16_f32 v212, v220, v221
	v_lshlrev_b32_e32 v210, 16, v133
	v_and_b32_e32 v211, 0xffff0000, v133
	v_pk_mul_f32 v[210:211], v[198:199], v[210:211]
	v_lshlrev_b32_e32 v222, 16, v129
	v_and_b32_e32 v223, 0xffff0000, v129
	v_pk_fma_f32 v[222:223], v[2:3], v[210:211], v[222:223]
	v_max3_f32 v197, v197, |v222|, |v223|
	v_pk_fma_f32 v[202:203], v[222:223], v[222:223], v[202:203]
	v_cvt_pk_bf16_f32 v213, v222, v223
	v_lshlrev_b32_e32 v208, 16, v134
	v_and_b32_e32 v209, 0xffff0000, v134
	v_pk_mul_f32 v[208:209], v[198:199], v[208:209]
	v_lshlrev_b32_e32 v224, 16, v130
	v_and_b32_e32 v225, 0xffff0000, v130
	v_pk_fma_f32 v[224:225], v[4:5], v[208:209], v[224:225]
	v_max3_f32 v197, v197, |v224|, |v225|
	v_pk_fma_f32 v[202:203], v[224:225], v[224:225], v[202:203]
	v_cvt_pk_bf16_f32 v214, v224, v225
	v_lshlrev_b32_e32 v210, 16, v135
	v_and_b32_e32 v211, 0xffff0000, v135
	v_pk_mul_f32 v[210:211], v[198:199], v[210:211]
	v_lshlrev_b32_e32 v226, 16, v131
	v_and_b32_e32 v227, 0xffff0000, v131
	v_pk_fma_f32 v[226:227], v[6:7], v[210:211], v[226:227]
	v_max3_f32 v197, v197, |v226|, |v227|
	v_pk_fma_f32 v[202:203], v[226:227], v[226:227], v[202:203]
	v_cvt_pk_bf16_f32 v215, v226, v227
	global_store_dwordx4 v192, v[212:215], s[80:81] offset:0 sc1 nt
	v_lshlrev_b32_e32 v208, 16, v140
	v_and_b32_e32 v209, 0xffff0000, v140
	v_pk_mul_f32 v[208:209], v[198:199], v[208:209]
	v_lshlrev_b32_e32 v128, 16, v136
	v_and_b32_e32 v129, 0xffff0000, v136
	v_pk_fma_f32 v[128:129], v[8:9], v[208:209], v[128:129]
	v_max3_f32 v197, v197, |v128|, |v129|
	v_pk_fma_f32 v[202:203], v[128:129], v[128:129], v[202:203]
	v_cvt_pk_bf16_f32 v246, v128, v129
	v_lshlrev_b32_e32 v210, 16, v141
	v_and_b32_e32 v211, 0xffff0000, v141
	v_pk_mul_f32 v[210:211], v[198:199], v[210:211]
	v_lshlrev_b32_e32 v130, 16, v137
	v_and_b32_e32 v131, 0xffff0000, v137
	v_pk_fma_f32 v[130:131], v[10:11], v[210:211], v[130:131]
	v_max3_f32 v197, v197, |v130|, |v131|
	v_pk_fma_f32 v[202:203], v[130:131], v[130:131], v[202:203]
	v_cvt_pk_bf16_f32 v247, v130, v131
	v_lshlrev_b32_e32 v208, 16, v142
	v_and_b32_e32 v209, 0xffff0000, v142
	v_pk_mul_f32 v[208:209], v[198:199], v[208:209]
	v_lshlrev_b32_e32 v132, 16, v138
	v_and_b32_e32 v133, 0xffff0000, v138
	v_pk_fma_f32 v[132:133], v[12:13], v[208:209], v[132:133]
	v_max3_f32 v197, v197, |v132|, |v133|
	v_pk_fma_f32 v[202:203], v[132:133], v[132:133], v[202:203]
	v_cvt_pk_bf16_f32 v248, v132, v133
	v_lshlrev_b32_e32 v210, 16, v143
	v_and_b32_e32 v211, 0xffff0000, v143
	v_pk_mul_f32 v[210:211], v[198:199], v[210:211]
	v_lshlrev_b32_e32 v134, 16, v139
	v_and_b32_e32 v135, 0xffff0000, v139
	v_pk_fma_f32 v[134:135], v[14:15], v[210:211], v[134:135]
	v_max3_f32 v197, v197, |v134|, |v135|
	v_pk_fma_f32 v[202:203], v[134:135], v[134:135], v[202:203]
	v_cvt_pk_bf16_f32 v249, v134, v135
	global_store_dwordx4 v192, v[246:249], s[80:81] offset:1024 sc1 nt
	v_lshlrev_b32_e32 v208, 16, v148
	v_and_b32_e32 v209, 0xffff0000, v148
	v_pk_mul_f32 v[208:209], v[198:199], v[208:209]
	v_lshlrev_b32_e32 v136, 16, v144
	v_and_b32_e32 v137, 0xffff0000, v144
	v_pk_fma_f32 v[136:137], v[16:17], v[208:209], v[136:137]
	v_max3_f32 v197, v197, |v136|, |v137|
	v_pk_fma_f32 v[202:203], v[136:137], v[136:137], v[202:203]
	v_cvt_pk_bf16_f32 v212, v136, v137
	v_lshlrev_b32_e32 v210, 16, v149
	v_and_b32_e32 v211, 0xffff0000, v149
	v_pk_mul_f32 v[210:211], v[198:199], v[210:211]
	v_lshlrev_b32_e32 v138, 16, v145
; template <int OFF = 0, class V> __device__ __forceinline__ void st_wt16(void* p, V v) { static_assert(sizeof(V) == 16, ""); asm volatile("global_store_dwordx4 %0, %1, off offset:%2 sc1\n\ts_nop 1" :: "v"(p), "v"(v), "i"(OFF)); }
; template <int OFF = 0, class V> __device__ __forceinline__ void st_wt8(void* p, V v) { static_assert(sizeof(V) == 8, ""); asm volatile("global_store_dwordx2 %0, %1, off offset:%2 sc1\n\ts_nop 1" :: "v"(p), "v"(v), "i"(OFF)); }
; __device__ __forceinline__ unsigned pk2(float lo, float hi) { return pg8::cvt_pk_bf16(lo, hi); }
; __device__ __forceinline__ float bf_lo(unsigned w) { return __uint_as_float(w << 16); }
; __device__ __forceinline__ float bf_hi(unsigned w) { return __uint_as_float(w & 0xffff0000u); }
; __device__ __forceinline__ void resid_rows(bf16* __restrict__ XB, const bf16* __restrict__ Y, const float* __restrict__ PART, const float* __restrict__ g, float* __restrict__ RS, ...
;     ...
;         for (int j = 0; j < 16; ++j) { const int c = (lane + 64 * j) * 4;
;             f32x4 o; o.x = bf_lo(xr[j].x) + bf_lo(yr[j].x) * ry * gv[j].x; o.y = bf_hi(xr[j].x) + bf_hi(yr[j].x) * ry * gv[j].y; o.z = bf_lo(xr[j].y) + bf_lo(yr[j].y) * ry * gv[j].z; o.w = bf_hi(xr[j].y) + bf_hi(yr[j].y) * ry * gv[j].w;
;             ss += (o.x * o.x + o.y * o.y) + (o.z * o.z + o.w * o.w); ov[j] = o; am = fmaxf(fmaxf(am, fmaxf(fabsf(o.x), fabsf(o.y))), fmaxf(fabsf(o.z), fabsf(o.w)));
;             if (outf) st_wt16(outf + (size_t)m * DM + c, o); else { v2u ob; ob.x = pk2(o.x, o.y); ob.y = pk2(o.z, o.w); st_wt8(xrow + c, ob); } }
	v_and_b32_e32 v139, 0xffff0000, v145
	v_pk_fma_f32 v[138:139], v[18:19], v[210:211], v[138:139]
	v_max3_f32 v197, v197, |v138|, |v139|
	v_pk_fma_f32 v[202:203], v[138:139], v[138:139], v[202:203]
	v_cvt_pk_bf16_f32 v213, v138, v139
	v_lshlrev_b32_e32 v208, 16, v150
	v_and_b32_e32 v209, 0xffff0000, v150
	v_pk_mul_f32 v[208:209], v[198:199], v[208:209]
	v_lshlrev_b32_e32 v140, 16, v146
	v_and_b32_e32 v141, 0xffff0000, v146
	v_pk_fma_f32 v[140:141], v[20:21], v[208:209], v[140:141]
	v_max3_f32 v197, v197, |v140|, |v141|
	v_pk_fma_f32 v[202:203], v[140:141], v[140:141], v[202:203]
	v_cvt_pk_bf16_f32 v214, v140, v141
	v_lshlrev_b32_e32 v210, 16, v151
	v_and_b32_e32 v211, 0xffff0000, v151
	v_pk_mul_f32 v[210:211], v[198:199], v[210:211]
	v_lshlrev_b32_e32 v142, 16, v147
	v_and_b32_e32 v143, 0xffff0000, v147
	v_pk_fma_f32 v[142:143], v[22:23], v[210:211], v[142:143]
	v_max3_f32 v197, v197, |v142|, |v143|
	v_pk_fma_f32 v[202:203], v[142:143], v[142:143], v[202:203]
	v_cvt_pk_bf16_f32 v215, v142, v143
	global_store_dwordx4 v192, v[212:215], s[80:81] offset:2048 sc1 nt
	v_lshlrev_b32_e32 v208, 16, v156
	v_and_b32_e32 v209, 0xffff0000, v156
	v_pk_mul_f32 v[208:209], v[198:199], v[208:209]
	v_lshlrev_b32_e32 v144, 16, v152
	v_and_b32_e32 v145, 0xffff0000, v152
	v_pk_fma_f32 v[144:145], v[24:25], v[208:209], v[144:145]
	v_max3_f32 v197, v197, |v144|, |v145|
	v_pk_fma_f32 v[202:203], v[144:145], v[144:145], v[202:203]
	v_cvt_pk_bf16_f32 v246, v144, v145
	v_lshlrev_b32_e32 v210, 16, v157
	v_and_b32_e32 v211, 0xffff0000, v157
	v_pk_mul_f32 v[210:211], v[198:199], v[210:211]
	v_lshlrev_b32_e32 v146, 16, v153
	v_and_b32_e32 v147, 0xffff0000, v153
	v_pk_fma_f32 v[146:147], v[26:27], v[210:211], v[146:147]
	v_max3_f32 v197, v197, |v146|, |v147|
	v_pk_fma_f32 v[202:203], v[146:147], v[146:147], v[202:203]
	v_cvt_pk_bf16_f32 v247, v146, v147
	v_lshlrev_b32_e32 v208, 16, v158
	v_and_b32_e32 v209, 0xffff0000, v158
	v_pk_mul_f32 v[208:209], v[198:199], v[208:209]
	v_lshlrev_b32_e32 v148, 16, v154
	v_and_b32_e32 v149, 0xffff0000, v154
	v_pk_fma_f32 v[148:149], v[28:29], v[208:209], v[148:149]
	v_max3_f32 v197, v197, |v148|, |v149|
	v_pk_fma_f32 v[202:203], v[148:149], v[148:149], v[202:203]
	v_cvt_pk_bf16_f32 v248, v148, v149
	v_lshlrev_b32_e32 v210, 16, v159
	v_and_b32_e32 v211, 0xffff0000, v159
	v_pk_mul_f32 v[210:211], v[198:199], v[210:211]
	v_lshlrev_b32_e32 v150, 16, v155
	v_and_b32_e32 v151, 0xffff0000, v155
	v_pk_fma_f32 v[150:151], v[30:31], v[210:211], v[150:151]
	v_max3_f32 v197, v197, |v150|, |v151|
	v_pk_fma_f32 v[202:203], v[150:151], v[150:151], v[202:203]
	v_cvt_pk_bf16_f32 v249, v150, v151
	global_store_dwordx4 v192, v[246:249], s[80:81] offset:3072 sc1 nt
	v_lshlrev_b32_e32 v208, 16, v164
	v_and_b32_e32 v209, 0xffff0000, v164
	v_pk_mul_f32 v[208:209], v[198:199], v[208:209]
	v_lshlrev_b32_e32 v152, 16, v160
	v_and_b32_e32 v153, 0xffff0000, v160
	v_pk_fma_f32 v[152:153], v[32:33], v[208:209], v[152:153]
	v_max3_f32 v197, v197, |v152|, |v153|
	v_pk_fma_f32 v[202:203], v[152:153], v[152:153], v[202:203]
	v_cvt_pk_bf16_f32 v212, v152, v153
	v_lshlrev_b32_e32 v210, 16, v165
	v_and_b32_e32 v211, 0xffff0000, v165
	v_pk_mul_f32 v[210:211], v[198:199], v[210:211]
	v_lshlrev_b32_e32 v154, 16, v161
	v_and_b32_e32 v155, 0xffff0000, v161
	v_pk_fma_f32 v[154:155], v[34:35], v[210:211], v[154:155]
	v_max3_f32 v197, v197, |v154|, |v155|
	v_pk_fma_f32 v[202:203], v[154:155], v[154:155], v[202:203]
	v_cvt_pk_bf16_f32 v213, v154, v155
	v_lshlrev_b32_e32 v208, 16, v166
	v_and_b32_e32 v209, 0xffff0000, v166
	v_pk_mul_f32 v[208:209], v[198:199], v[208:209]
	v_lshlrev_b32_e32 v156, 16, v162
	v_and_b32_e32 v157, 0xffff0000, v162
	v_pk_fma_f32 v[156:157], v[36:37], v[208:209], v[156:157]
	v_max3_f32 v197, v197, |v156|, |v157|
	v_pk_fma_f32 v[202:203], v[156:157], v[156:157], v[202:203]
	v_cvt_pk_bf16_f32 v214, v156, v157
	v_lshlrev_b32_e32 v210, 16, v167
	v_and_b32_e32 v211, 0xffff0000, v167
	v_pk_mul_f32 v[210:211], v[198:199], v[210:211]
	v_lshlrev_b32_e32 v158, 16, v163
	v_and_b32_e32 v159, 0xffff0000, v163
	v_pk_fma_f32 v[158:159], v[38:39], v[210:211], v[158:159]
	v_max3_f32 v197, v197, |v158|, |v159|
	v_pk_fma_f32 v[202:203], v[158:159], v[158:159], v[202:203]
	v_cvt_pk_bf16_f32 v215, v158, v159
	global_store_dwordx4 v193, v[212:215], s[80:81] offset:0 sc1 nt
	v_lshlrev_b32_e32 v208, 16, v172
	v_and_b32_e32 v209, 0xffff0000, v172
	v_pk_mul_f32 v[208:209], v[198:199], v[208:209]
	v_lshlrev_b32_e32 v160, 16, v168
	v_and_b32_e32 v161, 0xffff0000, v168
	v_pk_fma_f32 v[160:161], v[40:41], v[208:209], v[160:161]
	v_max3_f32 v197, v197, |v160|, |v161|
	v_pk_fma_f32 v[202:203], v[160:161], v[160:161], v[202:203]
	v_cvt_pk_bf16_f32 v246, v160, v161
	v_lshlrev_b32_e32 v210, 16, v173
	v_and_b32_e32 v211, 0xffff0000, v173
	v_pk_mul_f32 v[210:211], v[198:199], v[210:211]
	v_lshlrev_b32_e32 v162, 16, v169
	v_and_b32_e32 v163, 0xffff0000, v169
	v_pk_fma_f32 v[162:163], v[42:43], v[210:211], v[162:163]
	v_max3_f32 v197, v197, |v162|, |v163|
	v_pk_fma_f32 v[202:203], v[162:163], v[162:163], v[202:203]
	v_cvt_pk_bf16_f32 v247, v162, v163
	v_lshlrev_b32_e32 v208, 16, v174
	v_and_b32_e32 v209, 0xffff0000, v174
	v_pk_mul_f32 v[208:209], v[198:199], v[208:209]
	v_lshlrev_b32_e32 v164, 16, v170
	v_and_b32_e32 v165, 0xffff0000, v170
	v_pk_fma_f32 v[164:165], v[44:45], v[208:209], v[164:165]
	v_max3_f32 v197, v197, |v164|, |v165|
	v_pk_fma_f32 v[202:203], v[164:165], v[164:165], v[202:203]
	v_cvt_pk_bf16_f32 v248, v164, v165
	v_lshlrev_b32_e32 v210, 16, v175
	v_and_b32_e32 v211, 0xffff0000, v175
	v_pk_mul_f32 v[210:211], v[198:199], v[210:211]
	v_lshlrev_b32_e32 v166, 16, v171
; template <int OFF = 0, class V> __device__ __forceinline__ void st_wt16(void* p, V v) { static_assert(sizeof(V) == 16, ""); asm volatile("global_store_dwordx4 %0, %1, off offset:%2 sc1\n\ts_nop 1" :: "v"(p), "v"(v), "i"(OFF)); }
; template <int OFF = 0, class V> __device__ __forceinline__ void st_wt8(void* p, V v) { static_assert(sizeof(V) == 8, ""); asm volatile("global_store_dwordx2 %0, %1, off offset:%2 sc1\n\ts_nop 1" :: "v"(p), "v"(v), "i"(OFF)); }
; __device__ __forceinline__ void st_wt4(void* p, unsigned v) { asm volatile("global_store_dword %0, %1, off sc1\n\ts_nop 1" :: "v"(p), "v"(v)); }
; __device__ __forceinline__ unsigned pk2(float lo, float hi) { return pg8::cvt_pk_bf16(lo, hi); }
; __device__ __forceinline__ float bf_lo(unsigned w) { return __uint_as_float(w << 16); }
; __device__ __forceinline__ float bf_hi(unsigned w) { return __uint_as_float(w & 0xffff0000u); }
; __device__ __forceinline__ void resid_rows(bf16* __restrict__ XB, const bf16* __restrict__ Y, const float* __restrict__ PART, const float* __restrict__ g, float* __restrict__ RS, ...
;     ...
;         for (int j = 0; j < 16; ++j) { const int c = (lane + 64 * j) * 4;
;             f32x4 o; o.x = bf_lo(xr[j].x) + bf_lo(yr[j].x) * ry * gv[j].x; o.y = bf_hi(xr[j].x) + bf_hi(yr[j].x) * ry * gv[j].y; o.z = bf_lo(xr[j].y) + bf_lo(yr[j].y) * ry * gv[j].z; o.w = bf_hi(xr[j].y) + bf_hi(yr[j].y) * ry * gv[j].w;
;             ss += (o.x * o.x + o.y * o.y) + (o.z * o.z + o.w * o.w); ov[j] = o; am = fmaxf(fmaxf(am, fmaxf(fabsf(o.x), fabsf(o.y))), fmaxf(fabsf(o.z), fabsf(o.w)));
;             if (outf) st_wt16(outf + (size_t)m * DM + c, o); else { v2u ob; ob.x = pk2(o.x, o.y); ob.y = pk2(o.z, o.w); st_wt8(xrow + c, ob); } }
;         if (XQ) {
;             am = fmaxf(wave_max(am), 1e-20f); const float qs = 127.0f / am;
; #pragma unroll
;             for (int j = 0; j < 16; ++j) { const int q0 = (int)rintf(ov[j].x * qs), q1 = (int)rintf(ov[j].y * qs), q2 = (int)rintf(ov[j].z * qs), q3 = (int)rintf(ov[j].w * qs);
;                 st_wt4(XQ + (size_t)m * (DM / 4) + lane + 64 * j, ((unsigned)q0 & 255u) | (((unsigned)q1 & 255u) << 8) | (((unsigned)q2 & 255u) << 16) | ((unsigned)q3 << 24)); }
;             if (lane == 0) AS[m] = am * (1.0f / 127.0f); }
;         ss = wave_sum(ss);
	v_and_b32_e32 v167, 0xffff0000, v171
	v_pk_fma_f32 v[166:167], v[46:47], v[210:211], v[166:167]
	v_max3_f32 v197, v197, |v166|, |v167|
	v_pk_fma_f32 v[202:203], v[166:167], v[166:167], v[202:203]
	v_cvt_pk_bf16_f32 v249, v166, v167
	global_store_dwordx4 v193, v[246:249], s[80:81] offset:1024 sc1 nt
	v_lshlrev_b32_e32 v208, 16, v180
	v_and_b32_e32 v209, 0xffff0000, v180
	v_pk_mul_f32 v[208:209], v[198:199], v[208:209]
	v_lshlrev_b32_e32 v168, 16, v176
	v_and_b32_e32 v169, 0xffff0000, v176
	v_pk_fma_f32 v[168:169], v[48:49], v[208:209], v[168:169]
	v_max3_f32 v197, v197, |v168|, |v169|
	v_pk_fma_f32 v[202:203], v[168:169], v[168:169], v[202:203]
	v_cvt_pk_bf16_f32 v212, v168, v169
	v_lshlrev_b32_e32 v210, 16, v181
	v_and_b32_e32 v211, 0xffff0000, v181
	v_pk_mul_f32 v[210:211], v[198:199], v[210:211]
	v_lshlrev_b32_e32 v170, 16, v177
	v_and_b32_e32 v171, 0xffff0000, v177
	v_pk_fma_f32 v[170:171], v[50:51], v[210:211], v[170:171]
	v_max3_f32 v197, v197, |v170|, |v171|
	v_pk_fma_f32 v[202:203], v[170:171], v[170:171], v[202:203]
	v_cvt_pk_bf16_f32 v213, v170, v171
	v_lshlrev_b32_e32 v208, 16, v182
	v_and_b32_e32 v209, 0xffff0000, v182
	v_pk_mul_f32 v[208:209], v[198:199], v[208:209]
	v_lshlrev_b32_e32 v172, 16, v178
	v_and_b32_e32 v173, 0xffff0000, v178
	v_pk_fma_f32 v[172:173], v[52:53], v[208:209], v[172:173]
	v_max3_f32 v197, v197, |v172|, |v173|
	v_pk_fma_f32 v[202:203], v[172:173], v[172:173], v[202:203]
	v_cvt_pk_bf16_f32 v214, v172, v173
	v_lshlrev_b32_e32 v210, 16, v183
	v_and_b32_e32 v211, 0xffff0000, v183
	v_pk_mul_f32 v[210:211], v[198:199], v[210:211]
	v_lshlrev_b32_e32 v174, 16, v179
	v_and_b32_e32 v175, 0xffff0000, v179
	v_pk_fma_f32 v[174:175], v[54:55], v[210:211], v[174:175]
	v_max3_f32 v197, v197, |v174|, |v175|
	v_pk_fma_f32 v[202:203], v[174:175], v[174:175], v[202:203]
	v_cvt_pk_bf16_f32 v215, v174, v175
	global_store_dwordx4 v193, v[212:215], s[80:81] offset:2048 sc1 nt
	v_lshlrev_b32_e32 v208, 16, v188
	v_and_b32_e32 v209, 0xffff0000, v188
	v_pk_mul_f32 v[208:209], v[198:199], v[208:209]
	v_lshlrev_b32_e32 v176, 16, v184
	v_and_b32_e32 v177, 0xffff0000, v184
	v_pk_fma_f32 v[176:177], v[56:57], v[208:209], v[176:177]
	v_max3_f32 v197, v197, |v176|, |v177|
	v_pk_fma_f32 v[202:203], v[176:177], v[176:177], v[202:203]
	v_cvt_pk_bf16_f32 v246, v176, v177
	v_lshlrev_b32_e32 v210, 16, v189
	v_and_b32_e32 v211, 0xffff0000, v189
	v_pk_mul_f32 v[210:211], v[198:199], v[210:211]
	v_lshlrev_b32_e32 v178, 16, v185
	v_and_b32_e32 v179, 0xffff0000, v185
	v_pk_fma_f32 v[178:179], v[58:59], v[210:211], v[178:179]
	v_max3_f32 v197, v197, |v178|, |v179|
	v_pk_fma_f32 v[202:203], v[178:179], v[178:179], v[202:203]
	v_cvt_pk_bf16_f32 v247, v178, v179
	v_lshlrev_b32_e32 v208, 16, v190
	v_and_b32_e32 v209, 0xffff0000, v190
	v_pk_mul_f32 v[208:209], v[198:199], v[208:209]
	v_lshlrev_b32_e32 v180, 16, v186
	v_and_b32_e32 v181, 0xffff0000, v186
	v_pk_fma_f32 v[180:181], v[60:61], v[208:209], v[180:181]
	v_max3_f32 v197, v197, |v180|, |v181|
	v_pk_fma_f32 v[202:203], v[180:181], v[180:181], v[202:203]
	v_cvt_pk_bf16_f32 v248, v180, v181
	v_lshlrev_b32_e32 v210, 16, v191
	v_and_b32_e32 v211, 0xffff0000, v191
	v_pk_mul_f32 v[210:211], v[198:199], v[210:211]
	v_lshlrev_b32_e32 v182, 16, v187
	v_and_b32_e32 v183, 0xffff0000, v187
	v_pk_fma_f32 v[182:183], v[62:63], v[210:211], v[182:183]
	v_max3_f32 v197, v197, |v182|, |v183|
	v_pk_fma_f32 v[202:203], v[182:183], v[182:183], v[202:203]
	v_cvt_pk_bf16_f32 v249, v182, v183
	global_store_dwordx4 v193, v[246:249], s[80:81] offset:3072 sc1 nt
	v_add_f32_e32 v202, v202, v203
	s_waitcnt vmcnt(24)
	ds_swizzle_b32 v238, v197 offset:swizzle(SWAP,1)
	ds_swizzle_b32 v241, v202 offset:swizzle(SWAP,1)
	ds_swizzle_b32 v252, v250 offset:swizzle(SWAP,1)
	s_nop 0
	s_waitcnt lgkmcnt(0)
	v_max_f32_e32 v197, v197, v238
	v_add_f32_e32 v202, v202, v241
	v_add_f32_e32 v250, v250, v252
	ds_swizzle_b32 v238, v197 offset:swizzle(SWAP,2)
	ds_swizzle_b32 v241, v202 offset:swizzle(SWAP,2)
	ds_swizzle_b32 v252, v250 offset:swizzle(SWAP,2)
	s_nop 0
	s_waitcnt lgkmcnt(0)
	v_max_f32_e32 v197, v197, v238
	v_add_f32_e32 v202, v202, v241
	v_add_f32_e32 v250, v250, v252
	ds_swizzle_b32 v238, v197 offset:swizzle(SWAP,4)
	ds_swizzle_b32 v241, v202 offset:swizzle(SWAP,4)
	ds_swizzle_b32 v252, v250 offset:swizzle(SWAP,4)
	s_nop 0
	s_waitcnt lgkmcnt(0)
	v_max_f32_e32 v197, v197, v238
	v_add_f32_e32 v202, v202, v241
	v_add_f32_e32 v250, v250, v252
	ds_swizzle_b32 v238, v197 offset:swizzle(SWAP,8)
	ds_swizzle_b32 v241, v202 offset:swizzle(SWAP,8)
	ds_swizzle_b32 v252, v250 offset:swizzle(SWAP,8)
	s_nop 0
	s_waitcnt lgkmcnt(0)
	v_max_f32_e32 v197, v197, v238
	v_add_f32_e32 v202, v202, v241
	v_add_f32_e32 v250, v250, v252
	ds_swizzle_b32 v238, v197 offset:swizzle(SWAP,16)
	ds_swizzle_b32 v241, v202 offset:swizzle(SWAP,16)
	ds_swizzle_b32 v252, v250 offset:swizzle(SWAP,16)
	s_nop 0
	s_waitcnt lgkmcnt(0)
; template <int OFF = 0, class V> __device__ __forceinline__ void st_wt16(void* p, V v) { static_assert(sizeof(V) == 16, ""); asm volatile("global_store_dwordx4 %0, %1, off offset:%2 sc1\n\ts_nop 1" :: "v"(p), "v"(v), "i"(OFF)); }
; template <int OFF = 0, class V> __device__ __forceinline__ void st_wt8(void* p, V v) { static_assert(sizeof(V) == 8, ""); asm volatile("global_store_dwordx2 %0, %1, off offset:%2 sc1\n\ts_nop 1" :: "v"(p), "v"(v), "i"(OFF)); }
; __device__ __forceinline__ void st_wt4(void* p, unsigned v) { asm volatile("global_store_dword %0, %1, off sc1\n\ts_nop 1" :: "v"(p), "v"(v)); }
; __device__ __forceinline__ unsigned pk2(float lo, float hi) { return pg8::cvt_pk_bf16(lo, hi); }
; __device__ __forceinline__ float bf_lo(unsigned w) { return __uint_as_float(w << 16); }
; __device__ __forceinline__ void resid_rows(bf16* __restrict__ XB, const bf16* __restrict__ Y, const float* __restrict__ PART, const float* __restrict__ g, float* __restrict__ RS, ...
;     ...
;         const float ry = 1.0f / sqrtf(wave_sum(pv) * (1.0f / DM) + EPS);
;         float ss = 0.f, am = 0.f; f32x4 ov[16];
; #pragma unroll
;         for (int j = 0; j < 16; ++j) { const int c = (lane + 64 * j) * 4;
;             f32x4 o; o.x = bf_lo(xr[j].x) + bf_lo(yr[j].x) * ry * gv[j].x; o.y = bf_hi(xr[j].x) + bf_hi(yr[j].x) * ry * gv[j].y; o.z = bf_lo(xr[j].y) + bf_lo(yr[j].y) * ry * gv[j].z; o.w = bf_hi(xr[j].y) + bf_hi(yr[j].y) * ry * gv[j].w;
;             ss += (o.x * o.x + o.y * o.y) + (o.z * o.z + o.w * o.w); ov[j] = o; am = fmaxf(fmaxf(am, fmaxf(fabsf(o.x), fabsf(o.y))), fmaxf(fabsf(o.z), fabsf(o.w)));
;             if (outf) st_wt16(outf + (size_t)m * DM + c, o); else { v2u ob; ob.x = pk2(o.x, o.y); ob.y = pk2(o.z, o.w); st_wt8(xrow + c, ob); } }
;         if (XQ) {
;             am = fmaxf(wave_max(am), 1e-20f); const float qs = 127.0f / am;
; #pragma unroll
;             for (int j = 0; j < 16; ++j) { const int q0 = (int)rintf(ov[j].x * qs), q1 = (int)rintf(ov[j].y * qs), q2 = (int)rintf(ov[j].z * qs), q3 = (int)rintf(ov[j].w * qs);
;                 st_wt4(XQ + (size_t)m * (DM / 4) + lane + 64 * j, ((unsigned)q0 & 255u) | (((unsigned)q1 & 255u) << 8) | (((unsigned)q2 & 255u) << 16) | ((unsigned)q3 << 24)); }
;             if (lane == 0) AS[m] = am * (1.0f / 127.0f); }
;         ss = wave_sum(ss);
;         if (lane == 0) RS[m] = 1.0f / sqrtf(ss * (1.0f / DM) + EPS);
	v_max_f32_e32 v197, v197, v238
	v_add_f32_e32 v202, v202, v241
	v_add_f32_e32 v250, v250, v252
	v_mov_b32_e32 v238, v197
	v_mov_b32_e32 v241, v202
	v_mov_b32_e32 v252, v250
	s_nop 1
	v_permlane32_swap_b32_e32 v197, v238
	v_permlane32_swap_b32_e32 v202, v241
	v_permlane32_swap_b32_e32 v250, v252
	v_max3_f32 v197, v197, v238, s58
	v_add_f32_e32 v202, v202, v241
	v_add_f32_e32 v250, v250, v252
	v_div_scale_f32 v212, s[0:1], v197, v197, s57
	v_rcp_f32_e32 v213, v212
	s_nop 0
	v_fma_f32 v214, -v212, v213, 1.0
	v_fmac_f32_e32 v213, v214, v213
	v_div_scale_f32 v214, vcc, s57, v197, s57
	v_mul_f32_e32 v215, v214, v213
	v_fma_f32 v246, -v212, v215, v214
	v_fmac_f32_e32 v215, v246, v213
	v_fma_f32 v214, -v212, v215, v214
	v_div_fmas_f32 v214, v214, v213, v215
	v_div_fixup_f32 v204, v214, v197, s57
	v_mov_b32_e32 v205, v204
	v_fmamk_f32 v212, v250, 0x39800000, v216
	v_mul_f32_e32 v213, 0x4f800000, v212
	v_cmp_gt_f32_e32 vcc, s59, v212
	s_nop 1
	v_cndmask_b32_e32 v214, v212, v213, vcc
	v_sqrt_f32_e32 v215, v214
	s_nop 0
	s_nop 0
	v_add_u32_e32 v246, -1, v215
	v_fma_f32 v247, -v246, v215, v214
	v_cmp_ge_f32_e64 s[62:63], 0, v247
	v_add_u32_e32 v247, 1, v215
	v_fma_f32 v248, -v247, v215, v214
	v_cndmask_b32_e64 v246, v215, v246, s[62:63]
	v_cmp_lt_f32_e64 s[62:63], 0, v248
	s_nop 1
	v_cndmask_b32_e64 v246, v246, v247, s[62:63]
	v_mul_f32_e32 v247, 0x37800000, v246
	v_cndmask_b32_e32 v246, v246, v247, vcc
	v_cmp_class_f32_e32 vcc, v214, v239
	s_nop 1
	v_cndmask_b32_e32 v248, v246, v214, vcc
	v_div_scale_f32 v249, s[0:1], v248, v248, 1.0
	v_rcp_f32_e32 v212, v249
	s_nop 0
	v_fma_f32 v213, -v249, v212, 1.0
	v_fmac_f32_e32 v212, v213, v212
	v_div_scale_f32 v213, vcc, 1.0, v248, 1.0
	v_mul_f32_e32 v214, v213, v212
	v_fma_f32 v215, -v249, v214, v213
	v_fmac_f32_e32 v214, v215, v212
	v_fma_f32 v213, -v249, v214, v213
	v_div_fmas_f32 v213, v213, v212, v214
	v_div_fixup_f32 v200, v213, v248, 1.0
	v_fmamk_f32 v212, v202, 0x39800000, v216
	v_mul_f32_e32 v213, 0x4f800000, v212
	v_cmp_gt_f32_e32 vcc, s59, v212
	s_nop 1
	v_cndmask_b32_e32 v214, v212, v213, vcc
	v_sqrt_f32_e32 v215, v214
	s_nop 0
	s_nop 0
	v_add_u32_e32 v246, -1, v215
	v_fma_f32 v247, -v246, v215, v214
	v_cmp_ge_f32_e64 s[62:63], 0, v247
	v_add_u32_e32 v247, 1, v215
	v_fma_f32 v248, -v247, v215, v214
	v_cndmask_b32_e64 v246, v215, v246, s[62:63]
	v_cmp_lt_f32_e64 s[62:63], 0, v248
	s_nop 1
	v_cndmask_b32_e64 v246, v246, v247, s[62:63]
	v_mul_f32_e32 v247, 0x37800000, v246
	v_cndmask_b32_e32 v246, v246, v247, vcc
	v_cmp_class_f32_e32 vcc, v214, v239
	s_nop 1
	v_cndmask_b32_e32 v248, v246, v214, vcc
	v_div_scale_f32 v249, s[0:1], v248, v248, 1.0
	v_rcp_f32_e32 v212, v249
	s_nop 0
	v_fma_f32 v213, -v249, v212, 1.0
	v_fmac_f32_e32 v212, v213, v212
	v_div_scale_f32 v213, vcc, 1.0, v248, 1.0
	v_mul_f32_e32 v214, v213, v212
	v_fma_f32 v215, -v249, v214, v213
	v_fmac_f32_e32 v214, v215, v212
	v_fma_f32 v213, -v249, v214, v213
	v_div_fmas_f32 v213, v213, v212, v214
	v_div_fixup_f32 v241, v213, v248, 1.0
	v_mul_f32_e32 v238, 0x3c010204, v197
	v_pk_mul_f32 v[208:209], v[220:221], v[204:205]
	v_pk_mul_f32 v[210:211], v[222:223], v[204:205]
	v_pk_add_f32 v[208:209], v[208:209], v[206:207]
	v_pk_add_f32 v[210:211], v[210:211], v[206:207]
	v_perm_b32 v208, v209, v208, s60
	v_perm_b32 v210, v211, v210, s61
	v_or_b32_e32 v212, v208, v210
	v_pk_mul_f32 v[208:209], v[224:225], v[204:205]
	v_pk_mul_f32 v[210:211], v[226:227], v[204:205]
	v_pk_add_f32 v[208:209], v[208:209], v[206:207]
	v_pk_add_f32 v[210:211], v[210:211], v[206:207]
	v_perm_b32 v208, v209, v208, s60
	v_perm_b32 v210, v211, v210, s61
	v_or_b32_e32 v213, v208, v210
	global_store_dwordx2 v194, v[212:213], s[82:83] offset:0 sc1
	v_pk_mul_f32 v[208:209], v[128:129], v[204:205]
	v_pk_mul_f32 v[210:211], v[130:131], v[204:205]
	v_pk_add_f32 v[208:209], v[208:209], v[206:207]
	v_pk_add_f32 v[210:211], v[210:211], v[206:207]
	v_perm_b32 v208, v209, v208, s60
	v_perm_b32 v210, v211, v210, s61
	v_or_b32_e32 v246, v208, v210
	v_pk_mul_f32 v[208:209], v[132:133], v[204:205]
	v_pk_mul_f32 v[210:211], v[134:135], v[204:205]
	v_pk_add_f32 v[208:209], v[208:209], v[206:207]
	v_pk_add_f32 v[210:211], v[210:211], v[206:207]
	v_perm_b32 v208, v209, v208, s60
	v_perm_b32 v210, v211, v210, s61
; __device__ __forceinline__ void st_wt4(void* p, unsigned v) { asm volatile("global_store_dword %0, %1, off sc1\n\ts_nop 1" :: "v"(p), "v"(v)); }
; __device__ __forceinline__ void resid_rows(bf16* __restrict__ XB, const bf16* __restrict__ Y, const float* __restrict__ PART, const float* __restrict__ g, float* __restrict__ RS, ...
;     ...
;             for (int j = 0; j < 16; ++j) { const int q0 = (int)rintf(ov[j].x * qs), q1 = (int)rintf(ov[j].y * qs), q2 = (int)rintf(ov[j].z * qs), q3 = (int)rintf(ov[j].w * qs);
;                 st_wt4(XQ + (size_t)m * (DM / 4) + lane + 64 * j, ((unsigned)q0 & 255u) | (((unsigned)q1 & 255u) << 8) | (((unsigned)q2 & 255u) << 16) | ((unsigned)q3 << 24)); }
;             if (lane == 0) AS[m] = am * (1.0f / 127.0f); }
;         ss = wave_sum(ss);
;         if (lane == 0) RS[m] = 1.0f / sqrtf(ss * (1.0f / DM) + EPS);
;     }
	v_or_b32_e32 v247, v208, v210
	global_store_dwordx2 v194, v[246:247], s[82:83] offset:512 sc1
	v_pk_mul_f32 v[208:209], v[136:137], v[204:205]
	v_pk_mul_f32 v[210:211], v[138:139], v[204:205]
	v_pk_add_f32 v[208:209], v[208:209], v[206:207]
	v_pk_add_f32 v[210:211], v[210:211], v[206:207]
	v_perm_b32 v208, v209, v208, s60
	v_perm_b32 v210, v211, v210, s61
	v_or_b32_e32 v212, v208, v210
	v_pk_mul_f32 v[208:209], v[140:141], v[204:205]
	v_pk_mul_f32 v[210:211], v[142:143], v[204:205]
	v_pk_add_f32 v[208:209], v[208:209], v[206:207]
	v_pk_add_f32 v[210:211], v[210:211], v[206:207]
	v_perm_b32 v208, v209, v208, s60
	v_perm_b32 v210, v211, v210, s61
	v_or_b32_e32 v213, v208, v210
	global_store_dwordx2 v194, v[212:213], s[82:83] offset:1024 sc1
	v_pk_mul_f32 v[208:209], v[144:145], v[204:205]
	v_pk_mul_f32 v[210:211], v[146:147], v[204:205]
	v_pk_add_f32 v[208:209], v[208:209], v[206:207]
	v_pk_add_f32 v[210:211], v[210:211], v[206:207]
	v_perm_b32 v208, v209, v208, s60
	v_perm_b32 v210, v211, v210, s61
	v_or_b32_e32 v246, v208, v210
	v_pk_mul_f32 v[208:209], v[148:149], v[204:205]
	v_pk_mul_f32 v[210:211], v[150:151], v[204:205]
	v_pk_add_f32 v[208:209], v[208:209], v[206:207]
	v_pk_add_f32 v[210:211], v[210:211], v[206:207]
	v_perm_b32 v208, v209, v208, s60
	v_perm_b32 v210, v211, v210, s61
	v_or_b32_e32 v247, v208, v210
	global_store_dwordx2 v194, v[246:247], s[82:83] offset:1536 sc1
	v_pk_mul_f32 v[208:209], v[152:153], v[204:205]
	v_pk_mul_f32 v[210:211], v[154:155], v[204:205]
	v_pk_add_f32 v[208:209], v[208:209], v[206:207]
	v_pk_add_f32 v[210:211], v[210:211], v[206:207]
	v_perm_b32 v208, v209, v208, s60
	v_perm_b32 v210, v211, v210, s61
	v_or_b32_e32 v212, v208, v210
	v_pk_mul_f32 v[208:209], v[156:157], v[204:205]
	v_pk_mul_f32 v[210:211], v[158:159], v[204:205]
	v_pk_add_f32 v[208:209], v[208:209], v[206:207]
	v_pk_add_f32 v[210:211], v[210:211], v[206:207]
	v_perm_b32 v208, v209, v208, s60
	v_perm_b32 v210, v211, v210, s61
	v_or_b32_e32 v213, v208, v210
	global_store_dwordx2 v194, v[212:213], s[82:83] offset:2048 sc1
	v_pk_mul_f32 v[208:209], v[160:161], v[204:205]
	v_pk_mul_f32 v[210:211], v[162:163], v[204:205]
	v_pk_add_f32 v[208:209], v[208:209], v[206:207]
	v_pk_add_f32 v[210:211], v[210:211], v[206:207]
	v_perm_b32 v208, v209, v208, s60
	v_perm_b32 v210, v211, v210, s61
	v_or_b32_e32 v246, v208, v210
	v_pk_mul_f32 v[208:209], v[164:165], v[204:205]
	v_pk_mul_f32 v[210:211], v[166:167], v[204:205]
	v_pk_add_f32 v[208:209], v[208:209], v[206:207]
	v_pk_add_f32 v[210:211], v[210:211], v[206:207]
	v_perm_b32 v208, v209, v208, s60
	v_perm_b32 v210, v211, v210, s61
	v_or_b32_e32 v247, v208, v210
	global_store_dwordx2 v194, v[246:247], s[82:83] offset:2560 sc1
	v_pk_mul_f32 v[208:209], v[168:169], v[204:205]
	v_pk_mul_f32 v[210:211], v[170:171], v[204:205]
	v_pk_add_f32 v[208:209], v[208:209], v[206:207]
	v_pk_add_f32 v[210:211], v[210:211], v[206:207]
	v_perm_b32 v208, v209, v208, s60
	v_perm_b32 v210, v211, v210, s61
	v_or_b32_e32 v212, v208, v210
	v_pk_mul_f32 v[208:209], v[172:173], v[204:205]
	v_pk_mul_f32 v[210:211], v[174:175], v[204:205]
	v_pk_add_f32 v[208:209], v[208:209], v[206:207]
	v_pk_add_f32 v[210:211], v[210:211], v[206:207]
	v_perm_b32 v208, v209, v208, s60
	v_perm_b32 v210, v211, v210, s61
	v_or_b32_e32 v213, v208, v210
	global_store_dwordx2 v194, v[212:213], s[82:83] offset:3072 sc1
	v_pk_mul_f32 v[208:209], v[176:177], v[204:205]
	v_pk_mul_f32 v[210:211], v[178:179], v[204:205]
	v_pk_add_f32 v[208:209], v[208:209], v[206:207]
	v_pk_add_f32 v[210:211], v[210:211], v[206:207]
	v_perm_b32 v208, v209, v208, s60
	v_perm_b32 v210, v211, v210, s61
	v_or_b32_e32 v246, v208, v210
	v_pk_mul_f32 v[208:209], v[180:181], v[204:205]
	v_pk_mul_f32 v[210:211], v[182:183], v[204:205]
	v_pk_add_f32 v[208:209], v[208:209], v[206:207]
	v_pk_add_f32 v[210:211], v[210:211], v[206:207]
	v_perm_b32 v208, v209, v208, s60
	v_perm_b32 v210, v211, v210, s61
	v_or_b32_e32 v247, v208, v210
	global_store_dwordx2 v194, v[246:247], s[82:83] offset:3584 sc1
	s_mov_b64 exec, 1
	global_store_dword v196, v238, s[86:87]
	global_store_dword v196, v241, s[84:85]
	s_mov_b64 exec, -1
	s_mov_b32 s8, s9
	s_cmp_eq_u32 s16, 0
	s_cbranch_scc0 .Lr1_A_top
	s_branch .LBB0_818
